# phase-2 release: outputs stored write-through (sc1) + vmcnt(0) before the item barrier, per-item buffer_wbl2 removed
# speedup vs baseline: 1.0649x; 1.0276x over previous
; __device__ __forceinline__ unsigned cvtpk(float lo, float hi) { f32x2_t v = {lo, hi}; bf16x2_t b = __builtin_convertvector(v, bf16x2_t); return __builtin_bit_cast(unsigned, b); }
; template <bool SIGNAL>
; __device__ __forceinline__ void phase2(const Params& p, unsigned char* smem, const int lo, const int hi, const int worker, const int nworkers) {
;     ...
;         if (which < 2) {
;           float ss[4];
; #pragma unroll
;           for (int u = 0; u < 4; ++u) ss[u] = y0[u] * y0[u] + y1[u] * y1[u];
; #pragma unroll
;           for (int o = 32; o > 0; o >>= 1) {
; #pragma unroll
;             for (int u = 0; u < 4; ++u) ss[u] += __shfl_xor(ss[u], o);
;           }
; #pragma unroll
;           for (int u = 0; u < 4; ++u) {
;             const int r = wave * 16 + rb * 4 + u;
;             const bool pad = (c == 0 && r < 48);
;             float sc = rsqrtf(ss[u] + 1e-6f) * (which == 0 ? 0.08838834764831845f : 1.f);
;             if (pad) sc = 0.f;
;             unsigned pk = cvtpk(y0[u] * sc, y1[u] * sc);
;             *(unsigned*)(X + r * 128 + d0) = pk;
;             *(unsigned*)((which == 0 ? sq : sk) + r * 136 + d0) = pk;
;           }
;     ...
;       if (which == 2) {
; #pragma unroll
;         for (int i = 0; i < 4; ++i) { int idx = tid + 256 * i; int e = idx >> 3, c8 = (idx & 7) * 8; *(uint4*)(X + e * 64 + c8) = *(const uint4*)(svT + e * 72 + c8); }
;       }
.LBB0_289:
	s_and_b64 vcc, exec, s[38:39]
	s_cbranch_vccz .LBB0_278
	v_and_b32_e32 v166, 64, v163
	v_add_u32_e32 v168, 64, v166
	v_xor_b32_e32 v166, 32, v163
	v_cmp_lt_i32_e32 vcc, v166, v168
	v_pk_mul_f32 v[28:29], v[10:11], v[10:11]
	v_pk_mul_f32 v[30:31], v[12:13], v[12:13]
	v_cndmask_b32_e32 v166, v163, v166, vcc
	v_lshlrev_b32_e32 v170, 2, v166
	v_mov_b32_e32 v166, v30
	v_mov_b32_e32 v167, v28
	v_mov_b32_e32 v28, v31
	v_pk_add_f32 v[28:29], v[166:167], v[28:29]
	ds_bpermute_b32 v31, v170, v29
	ds_bpermute_b32 v30, v170, v28
	v_xor_b32_e32 v166, 16, v163
	v_cmp_lt_i32_e32 vcc, v166, v168
	v_cmp_gt_i32_e64 s[38:39], 48, v27
	v_cmp_gt_i32_e64 s[42:43], 48, v26
	v_cndmask_b32_e32 v166, v163, v166, vcc
	v_lshlrev_b32_e32 v171, 2, v166
	s_waitcnt lgkmcnt(0)
	v_pk_add_f32 v[28:29], v[28:29], v[30:31]
	ds_bpermute_b32 v31, v171, v29
	ds_bpermute_b32 v30, v171, v28
	v_xor_b32_e32 v166, 8, v163
	v_cmp_lt_i32_e32 vcc, v166, v168
	s_and_b64 s[38:39], s[68:69], s[38:39]
	s_waitcnt lgkmcnt(0)
	v_pk_add_f32 v[28:29], v[28:29], v[30:31]
	v_cndmask_b32_e32 v166, v163, v166, vcc
	v_lshlrev_b32_e32 v172, 2, v166
	ds_bpermute_b32 v31, v172, v29
	ds_bpermute_b32 v30, v172, v28
	v_xor_b32_e32 v166, 4, v163
	v_cmp_lt_i32_e32 vcc, v166, v168
	s_waitcnt lgkmcnt(0)
	v_pk_add_f32 v[28:29], v[28:29], v[30:31]
	v_cndmask_b32_e32 v166, v163, v166, vcc
	v_lshlrev_b32_e32 v173, 2, v166
	ds_bpermute_b32 v31, v173, v29
	ds_bpermute_b32 v30, v173, v28
	v_xor_b32_e32 v166, 2, v163
	v_cmp_lt_i32_e32 vcc, v166, v168
	s_waitcnt lgkmcnt(0)
	v_pk_add_f32 v[28:29], v[28:29], v[30:31]
	v_cndmask_b32_e32 v166, v163, v166, vcc
	v_lshlrev_b32_e32 v174, 2, v166
	ds_bpermute_b32 v31, v174, v29
	ds_bpermute_b32 v30, v174, v28
	v_xor_b32_e32 v166, 1, v163
	v_cmp_lt_i32_e32 vcc, v166, v168
	v_pk_mul_f32 v[168:169], v[16:17], v[16:17]
	s_waitcnt lgkmcnt(0)
	v_pk_add_f32 v[28:29], v[28:29], v[30:31]
	v_cndmask_b32_e32 v166, v163, v166, vcc
	v_lshlrev_b32_e32 v175, 2, v166
	ds_bpermute_b32 v31, v175, v29
	ds_bpermute_b32 v30, v175, v28
	v_pk_mul_f32 v[166:167], v[14:15], v[14:15]
	s_waitcnt lgkmcnt(0)
	v_pk_add_f32 v[28:29], v[28:29], v[30:31]
	v_mov_b32_e32 v30, v168
	v_mov_b32_e32 v31, v166
	v_mov_b32_e32 v166, v169
	v_pk_add_f32 v[30:31], v[30:31], v[166:167]
	ds_bpermute_b32 v167, v170, v31
	ds_bpermute_b32 v166, v170, v30
	v_pk_add_f32 v[28:29], v[28:29], s[64:65] op_sel_hi:[1,0]
	s_waitcnt lgkmcnt(0)
	v_pk_add_f32 v[30:31], v[30:31], v[166:167]
	v_mul_f32_e32 v27, 0x4b800000, v29
	v_cmp_gt_f32_e32 vcc, s88, v29
	ds_bpermute_b32 v167, v171, v31
	ds_bpermute_b32 v166, v171, v30
	v_cndmask_b32_e32 v27, v29, v27, vcc
	v_rsq_f32_e32 v27, v27
	s_nop 0
	v_mul_f32_e32 v26, 0x45800000, v27
	v_cndmask_b32_e32 v26, v27, v26, vcc
	v_mul_f32_e32 v29, v18, v26
	s_waitcnt lgkmcnt(0)
	v_pk_add_f32 v[26:27], v[30:31], v[166:167]
	ds_bpermute_b32 v31, v172, v27
	ds_bpermute_b32 v30, v172, v26
	v_cndmask_b32_e64 v166, v29, 0, s[38:39]
	v_pk_mul_f32 v[10:11], v[10:11], v[166:167] op_sel_hi:[1,0]
	v_cmp_gt_f32_e32 vcc, s88, v28
	v_cvt_pk_bf16_f32 v29, v10, v11
	s_waitcnt lgkmcnt(0)
	v_pk_add_f32 v[10:11], v[26:27], v[30:31]
	ds_bpermute_b32 v27, v173, v11
	ds_bpermute_b32 v26, v173, v10
	v_mul_f32_e32 v30, 0x4b800000, v28
	v_cndmask_b32_e32 v28, v28, v30, vcc
	v_rsq_f32_e32 v28, v28
	s_and_b64 s[38:39], s[68:69], s[42:43]
	s_waitcnt lgkmcnt(0)
	v_pk_add_f32 v[10:11], v[10:11], v[26:27]
	ds_bpermute_b32 v27, v174, v11
	ds_bpermute_b32 v26, v174, v10
	v_mul_f32_e32 v30, 0x45800000, v28
	v_cndmask_b32_e32 v28, v28, v30, vcc
	v_mul_f32_e32 v28, v18, v28
	v_cndmask_b32_e64 v28, v28, 0, s[38:39]
	s_waitcnt lgkmcnt(0)
	v_pk_add_f32 v[10:11], v[10:11], v[26:27]
	ds_bpermute_b32 v27, v175, v11
	ds_bpermute_b32 v26, v175, v10
	v_pk_mul_f32 v[12:13], v[12:13], v[28:29] op_sel_hi:[1,0]
	v_cmp_gt_i32_e64 s[38:39], 48, v23
	v_cvt_pk_bf16_f32 v12, v12, v13
	global_store_dword v[8:9], v12, off offset:-256 sc1
	s_waitcnt lgkmcnt(0)
	v_pk_add_f32 v[10:11], v[10:11], v[26:27]
	ds_write2_b32 v19, v29, v12 offset1:68
	v_pk_add_f32 v[10:11], v[10:11], s[64:65] op_sel_hi:[1,0]
	s_and_b64 s[38:39], s[68:69], s[38:39]
	v_mul_f32_e32 v13, 0x4b800000, v11
	v_cmp_gt_f32_e32 vcc, s88, v11
	v_cmp_gt_i32_e64 s[42:43], 48, v25
	global_store_dword v[8:9], v29, off offset:-512 sc1
	v_cndmask_b32_e32 v11, v11, v13, vcc
	v_rsq_f32_e32 v11, v11
	s_nop 0
	v_mul_f32_e32 v12, 0x45800000, v11
	v_cndmask_b32_e32 v11, v11, v12, vcc
	v_mul_f32_e32 v11, v18, v11
	v_cndmask_b32_e64 v12, v11, 0, s[38:39]
	v_mul_f32_e32 v11, 0x4b800000, v10
	v_cmp_gt_f32_e32 vcc, s88, v10
	s_and_b64 s[38:39], s[68:69], s[42:43]
	s_nop 0
	v_cndmask_b32_e32 v10, v10, v11, vcc
	v_rsq_f32_e32 v13, v10
	s_nop 0
	v_pk_mul_f32 v[10:11], v[14:15], v[12:13] op_sel_hi:[1,0]
	s_nop 0
	v_cvt_pk_bf16_f32 v12, v10, v11
	v_mul_f32_e32 v10, 0x45800000, v13
	v_cndmask_b32_e32 v10, v13, v10, vcc
	v_mul_f32_e32 v10, v18, v10
	v_cndmask_b32_e64 v10, v10, 0, s[38:39]
	v_pk_mul_f32 v[10:11], v[16:17], v[10:11] op_sel_hi:[1,0]
	global_store_dword v[8:9], v12, off sc1
	v_cvt_pk_bf16_f32 v10, v10, v11
	global_store_dword v[8:9], v10, off offset:256 sc1
	ds_write2_b32 v19, v12, v10 offset0:136 offset1:204
	s_branch .LBB0_278
.LBB0_291:
	s_cmp_lg_u32 s99, 2
	s_waitcnt lgkmcnt(0)
	s_barrier
	s_cbranch_scc1 .LBB0_261
	v_lshlrev_b32_e32 v0, 1, v38
	v_mov_b32_e32 v1, v35
	v_lshl_add_u64 v[0:1], s[80:81], 0, v[0:1]
	v_lshl_add_u64 v[4:5], v[62:63], 1, v[0:1]
	v_lshl_add_u64 v[6:7], v[64:65], 1, v[0:1]
	v_lshl_add_u64 v[8:9], v[66:67], 1, v[0:1]
	v_lshl_add_u64 v[10:11], v[68:69], 1, v[0:1]
	ds_read_b128 v[0:3], v119
	s_waitcnt lgkmcnt(0)
	global_store_dwordx4 v[4:5], v[0:3], off sc1
	ds_read_b128 v[0:3], v120
	s_waitcnt lgkmcnt(0)
	global_store_dwordx4 v[6:7], v[0:3], off sc1
	ds_read_b128 v[0:3], v121
	s_waitcnt lgkmcnt(0)
	global_store_dwordx4 v[8:9], v[0:3], off sc1
	ds_read_b128 v[0:3], v122
	s_waitcnt lgkmcnt(0)
	global_store_dwordx4 v[10:11], v[0:3], off sc1
	s_branch .LBB0_261

; __device__ __forceinline__ u16 f2bf(float f) { return (u16)(cvtpk(f, 0.f) & 0xffffu); }
; __device__ __forceinline__ f32x16 mfma32(bf16x8 a, bf16x8 b, f32x16 c) { return __builtin_amdgcn_mfma_f32_32x32x16_bf16(a, b, c, 0, 0, 0); }
; template <bool SIGNAL>
; __device__ __forceinline__ void phase2(const Params& p, unsigned char* smem, const int lo, const int hi, const int worker, const int nworkers) {
;     ...
;     const int ti = wave >> 1, tj = wave & 1;
;     f32x16 kk, qk;
; #pragma unroll
;     for (int r = 0; r < 16; ++r) { kk[r] = 0.f; qk[r] = 0.f; }
; #pragma unroll
;     for (int s = 0; s < 8; ++s) {
;       bf16x8 bj = *(const bf16x8*)(sk + (32 * tj + l31) * 136 + s * 16 + hf * 8);
;       bf16x8 ak = *(const bf16x8*)(sk + (32 * ti + l31) * 136 + s * 16 + hf * 8);
;       bf16x8 aq = *(const bf16x8*)(sq + (32 * ti + l31) * 136 + s * 16 + hf * 8);
;       kk = mfma32(ak, bj, kk); qk = mfma32(aq, bj, qk);
;     }
;     __syncthreads();
;     u16* Tg = TA + (size_t)it * 8704; u16* Ag = Tg + 4096; float* SCg = (float*)(Tg + 8192);
;     {
;       const int j = 32 * tj + l31; const float gcj = sgc[j];
; #pragma unroll
;       for (int r = 0; r < 16; ++r) {
;         const int i = 32 * ti + 8 * (r >> 2) + 4 * hf + (r & 3);
;         const float gci = sgc[i]; const float bi = sbeta[i];
;         const float dec = __expf(gci - gcj);
;         sM[i * 68 + j] = (j < i) ? bi * kk[r] * dec : 0.f;
;         Ag[i * 64 + j] = f2bf((j <= i) ? qk[r] * dec : 0.f);
;       }
;     }
.LBB0_298:
	ds_read_b128 v[0:3], v109 offset:51712
	ds_read_b128 v[4:7], v108 offset:51712
	ds_read_b128 v[166:169], v108 offset:51744
	s_mul_hi_i32 s36, s91, 0x4400
	s_mulk_i32 s91, 0x4400
	v_readlane_b32 s37, v247, 7
	s_waitcnt lgkmcnt(1)
	v_mfma_f32_32x32x16_bf16 v[16:31], v[0:3], v[4:7], 0
	ds_read_b128 v[0:3], v109 offset:34304
	ds_read_b128 v[170:173], v109 offset:34336
	ds_read_b128 v[174:177], v109 offset:51744
	s_add_u32 s38, s37, s91
	v_readlane_b32 s37, v247, 8
	s_addc_u32 s39, s37, s36
	s_add_u32 s42, s38, 0x2000
	v_readlane_b32 s36, v247, 45
	s_waitcnt lgkmcnt(2)
	v_mfma_f32_32x32x16_bf16 v[0:15], v[0:3], v[4:7], 0
	s_addc_u32 s43, s39, 0
	v_readlane_b32 s37, v247, 46
	s_waitcnt lgkmcnt(0)
	v_mfma_f32_32x32x16_bf16 v[16:31], v[174:177], v[166:169], v[16:31]
	v_mfma_f32_32x32x16_bf16 v[0:15], v[170:173], v[166:169], v[0:15]
	ds_read_b128 v[166:169], v108 offset:51776
	ds_read_b128 v[170:173], v109 offset:51776
	ds_read_b128 v[174:177], v109 offset:34368
	s_waitcnt lgkmcnt(1)
	v_mfma_f32_32x32x16_bf16 v[16:31], v[170:173], v[166:169], v[16:31]
	s_waitcnt lgkmcnt(0)
	v_mfma_f32_32x32x16_bf16 v[0:15], v[174:177], v[166:169], v[0:15]
	ds_read_b128 v[166:169], v108 offset:51808
	ds_read_b128 v[170:173], v109 offset:51808
	ds_read_b128 v[174:177], v109 offset:34400
	s_waitcnt lgkmcnt(1)
	v_mfma_f32_32x32x16_bf16 v[16:31], v[170:173], v[166:169], v[16:31]
	s_waitcnt lgkmcnt(0)
	v_mfma_f32_32x32x16_bf16 v[0:15], v[174:177], v[166:169], v[0:15]
	ds_read_b128 v[166:169], v108 offset:51840
	ds_read_b128 v[170:173], v109 offset:51840
	ds_read_b128 v[174:177], v109 offset:34432
	s_waitcnt lgkmcnt(1)
	v_mfma_f32_32x32x16_bf16 v[16:31], v[170:173], v[166:169], v[16:31]
	s_waitcnt lgkmcnt(0)
	v_mfma_f32_32x32x16_bf16 v[0:15], v[174:177], v[166:169], v[0:15]
	ds_read_b128 v[166:169], v108 offset:51872
	ds_read_b128 v[170:173], v109 offset:51872
	ds_read_b128 v[174:177], v109 offset:34464
	s_waitcnt lgkmcnt(1)
	v_mfma_f32_32x32x16_bf16 v[16:31], v[170:173], v[166:169], v[16:31]
	s_waitcnt lgkmcnt(0)
	v_mfma_f32_32x32x16_bf16 v[0:15], v[174:177], v[166:169], v[0:15]
	ds_read_b128 v[166:169], v108 offset:51904
	ds_read_b128 v[170:173], v109 offset:51904
	ds_read_b128 v[174:177], v109 offset:34496
	s_waitcnt lgkmcnt(1)
	v_mfma_f32_32x32x16_bf16 v[16:31], v[170:173], v[166:169], v[16:31]
	s_waitcnt lgkmcnt(0)
	v_mfma_f32_32x32x16_bf16 v[0:15], v[174:177], v[166:169], v[0:15]
	ds_read_b128 v[166:169], v108 offset:51936
	ds_read_b128 v[170:173], v109 offset:51936
	ds_read_b128 v[174:177], v109 offset:34528
	s_waitcnt lgkmcnt(0)
	s_barrier
	v_mfma_f32_32x32x16_bf16 v[16:31], v[170:173], v[166:169], v[16:31]
	v_mfma_f32_32x32x16_bf16 v[0:15], v[174:177], v[166:169], v[0:15]
	ds_read_b32 v166, v110
	ds_read_b32 v167, v123
	ds_read_b32 v168, v124
	s_waitcnt lgkmcnt(1)
	v_sub_f32_e32 v167, v167, v166
	v_mul_f32_e32 v167, 0x3fb8aa3b, v167
	v_exp_f32_e32 v167, v167
	s_waitcnt lgkmcnt(0)
	s_nop 2
	v_mul_f32_e32 v16, v16, v168
	v_lshl_add_u64 v[168:169], v[70:71], 1, s[42:43]
	v_mul_f32_e32 v0, v0, v167
	v_mul_f32_e32 v16, v16, v167
	v_cvt_pk_bf16_f32 v0, v0, s0
	v_cndmask_b32_e64 v16, 0, v16, s[36:37]
	v_cndmask_b32_e64 v0, v0, 0, s[66:67]
	ds_write_b32 v162, v16
	global_store_short v[168:169], v0, off sc1
	ds_read_b32 v0, v125
	ds_read_b32 v16, v126
	v_readlane_b32 s36, v247, 47
	v_readlane_b32 s37, v247, 48
	s_waitcnt lgkmcnt(1)
	v_sub_f32_e32 v0, v0, v166
	v_mul_f32_e32 v0, 0x3fb8aa3b, v0
	v_exp_f32_e32 v0, v0
	s_waitcnt lgkmcnt(0)
	v_mul_f32_e32 v16, v17, v16
	v_mul_f32_e32 v16, v16, v0
	v_mul_f32_e32 v0, v1, v0
	v_cndmask_b32_e64 v16, v16, 0, s[66:67]
	v_cvt_pk_bf16_f32 v0, v0, s0
	ds_write_b32 v162, v16 offset:272
	v_cndmask_b32_e64 v16, v0, 0, s[36:37]
	v_lshl_add_u64 v[0:1], v[72:73], 1, s[42:43]
	global_store_short v[0:1], v16, off sc1
	ds_read_b32 v0, v127
	ds_read_b32 v1, v128
	v_readlane_b32 s36, v247, 49
	v_readlane_b32 s37, v247, 50
	s_waitcnt lgkmcnt(1)
	v_sub_f32_e32 v0, v0, v166
	v_mul_f32_e32 v0, 0x3fb8aa3b, v0
	v_exp_f32_e32 v0, v0
	s_waitcnt lgkmcnt(0)
	v_mul_f32_e32 v1, v18, v1
	v_mul_f32_e32 v1, v1, v0
	v_cndmask_b32_e64 v1, 0, v1, s[36:37]
	v_mul_f32_e32 v0, v2, v0
	v_readlane_b32 s36, v247, 51
	v_cvt_pk_bf16_f32 v0, v0, s0
	v_readlane_b32 s37, v247, 52
	ds_write_b32 v162, v1 offset:544
	s_nop 0
	v_cndmask_b32_e64 v2, v0, 0, s[36:37]
	v_lshl_add_u64 v[0:1], v[74:75], 1, s[42:43]
	global_store_short v[0:1], v2, off sc1
	ds_read_b32 v0, v129
	ds_read_b32 v1, v130
	v_readlane_b32 s36, v247, 53
	v_readlane_b32 s37, v247, 54
	s_waitcnt lgkmcnt(1)
	v_sub_f32_e32 v0, v0, v166
	v_mul_f32_e32 v0, 0x3fb8aa3b, v0
	v_exp_f32_e32 v0, v0
	s_waitcnt lgkmcnt(0)
	v_mul_f32_e32 v1, v19, v1
	v_mul_f32_e32 v1, v1, v0
	v_cndmask_b32_e64 v1, 0, v1, s[36:37]
	v_mul_f32_e32 v0, v3, v0
	v_readlane_b32 s36, v247, 55
	v_cvt_pk_bf16_f32 v0, v0, s0
	v_readlane_b32 s37, v247, 56
	ds_write_b32 v162, v1 offset:816
	s_nop 0
	v_cndmask_b32_e64 v2, v0, 0, s[36:37]
	v_lshl_add_u64 v[0:1], v[76:77], 1, s[42:43]
	global_store_short v[0:1], v2, off sc1
	ds_read_b32 v0, v131
	ds_read_b32 v1, v132
	v_readlane_b32 s36, v247, 57
	v_readlane_b32 s37, v247, 58
	s_waitcnt lgkmcnt(1)
	v_sub_f32_e32 v0, v0, v166
	v_mul_f32_e32 v0, 0x3fb8aa3b, v0
	v_exp_f32_e32 v0, v0
	s_waitcnt lgkmcnt(0)
	v_mul_f32_e32 v1, v20, v1
	v_mul_f32_e32 v1, v1, v0
	v_cndmask_b32_e64 v1, 0, v1, s[36:37]
	v_mul_f32_e32 v0, v4, v0
	v_readlane_b32 s36, v246, 1
	v_cvt_pk_bf16_f32 v0, v0, s0
	v_readlane_b32 s37, v246, 2
	ds_write_b32 v162, v1 offset:2176
	s_nop 0
	v_cndmask_b32_e64 v2, v0, 0, s[36:37]
	v_lshl_add_u64 v[0:1], v[78:79], 1, s[42:43]
	global_store_short v[0:1], v2, off sc1
	ds_read_b32 v0, v133
	ds_read_b32 v1, v134
	v_readlane_b32 s36, v246, 3
	v_readlane_b32 s37, v246, 4
	s_waitcnt lgkmcnt(1)
; __device__ __forceinline__ u16 f2bf(float f) { return (u16)(cvtpk(f, 0.f) & 0xffffu); }
; template <bool SIGNAL>
; __device__ __forceinline__ void phase2(const Params& p, unsigned char* smem, const int lo, const int hi, const int worker, const int nworkers) {
;     ...
;       const int j = 32 * tj + l31; const float gcj = sgc[j];
; #pragma unroll
;       for (int r = 0; r < 16; ++r) {
;         const int i = 32 * ti + 8 * (r >> 2) + 4 * hf + (r & 3);
;         const float gci = sgc[i]; const float bi = sbeta[i];
;         const float dec = __expf(gci - gcj);
;         sM[i * 68 + j] = (j < i) ? bi * kk[r] * dec : 0.f;
;         Ag[i * 64 + j] = f2bf((j <= i) ? qk[r] * dec : 0.f);
;       }
;     }
;     __syncthreads();
	v_sub_f32_e32 v0, v0, v166
	v_mul_f32_e32 v0, 0x3fb8aa3b, v0
	v_exp_f32_e32 v0, v0
	s_waitcnt lgkmcnt(0)
	v_mul_f32_e32 v1, v21, v1
	v_mul_f32_e32 v1, v1, v0
	v_cndmask_b32_e64 v1, 0, v1, s[36:37]
	v_mul_f32_e32 v0, v5, v0
	v_readlane_b32 s36, v246, 5
	v_cvt_pk_bf16_f32 v0, v0, s0
	v_readlane_b32 s37, v246, 6
	ds_write_b32 v162, v1 offset:2448
	s_nop 0
	v_cndmask_b32_e64 v2, v0, 0, s[36:37]
	v_lshl_add_u64 v[0:1], v[80:81], 1, s[42:43]
	global_store_short v[0:1], v2, off sc1
	ds_read_b32 v0, v135
	ds_read_b32 v1, v136
	v_readlane_b32 s36, v246, 7
	v_readlane_b32 s37, v246, 8
	s_waitcnt lgkmcnt(1)
	v_sub_f32_e32 v0, v0, v166
	v_mul_f32_e32 v0, 0x3fb8aa3b, v0
	v_exp_f32_e32 v0, v0
	s_waitcnt lgkmcnt(0)
	v_mul_f32_e32 v1, v22, v1
	v_mul_f32_e32 v1, v1, v0
	v_cndmask_b32_e64 v1, 0, v1, s[36:37]
	v_mul_f32_e32 v0, v6, v0
	v_readlane_b32 s36, v246, 9
	v_cvt_pk_bf16_f32 v0, v0, s0
	v_readlane_b32 s37, v246, 10
	ds_write_b32 v162, v1 offset:2720
	s_nop 0
	v_cndmask_b32_e64 v2, v0, 0, s[36:37]
	v_lshl_add_u64 v[0:1], v[82:83], 1, s[42:43]
	global_store_short v[0:1], v2, off sc1
	ds_read_b32 v0, v137
	ds_read_b32 v1, v138
	v_readlane_b32 s36, v246, 11
	v_readlane_b32 s37, v246, 12
	s_waitcnt lgkmcnt(1)
	v_sub_f32_e32 v0, v0, v166
	v_mul_f32_e32 v0, 0x3fb8aa3b, v0
	v_exp_f32_e32 v0, v0
	s_waitcnt lgkmcnt(0)
	v_mul_f32_e32 v1, v23, v1
	v_mul_f32_e32 v1, v1, v0
	v_cndmask_b32_e64 v1, 0, v1, s[36:37]
	v_mul_f32_e32 v0, v7, v0
	v_readlane_b32 s36, v246, 13
	v_cvt_pk_bf16_f32 v0, v0, s0
	v_readlane_b32 s37, v246, 14
	ds_write_b32 v162, v1 offset:2992
	s_nop 0
	v_cndmask_b32_e64 v2, v0, 0, s[36:37]
	v_lshl_add_u64 v[0:1], v[84:85], 1, s[42:43]
	global_store_short v[0:1], v2, off sc1
	ds_read_b32 v0, v139
	ds_read_b32 v1, v140
	v_readlane_b32 s36, v246, 15
	v_readlane_b32 s37, v246, 16
	s_waitcnt lgkmcnt(1)
	v_sub_f32_e32 v0, v0, v166
	v_mul_f32_e32 v0, 0x3fb8aa3b, v0
	v_exp_f32_e32 v0, v0
	s_waitcnt lgkmcnt(0)
	v_mul_f32_e32 v1, v24, v1
	v_mul_f32_e32 v1, v1, v0
	v_cndmask_b32_e64 v1, 0, v1, s[36:37]
	v_mul_f32_e32 v0, v8, v0
	v_readlane_b32 s36, v246, 17
	v_cvt_pk_bf16_f32 v0, v0, s0
	v_readlane_b32 s37, v246, 18
	ds_write_b32 v162, v1 offset:4352
	s_nop 0
	v_cndmask_b32_e64 v2, v0, 0, s[36:37]
	v_lshl_add_u64 v[0:1], v[86:87], 1, s[42:43]
	global_store_short v[0:1], v2, off sc1
	ds_read_b32 v0, v141
	ds_read_b32 v1, v142
	v_readlane_b32 s36, v246, 19
	v_readlane_b32 s37, v246, 20
	s_waitcnt lgkmcnt(1)
	v_sub_f32_e32 v0, v0, v166
	v_mul_f32_e32 v0, 0x3fb8aa3b, v0
	v_exp_f32_e32 v0, v0
	s_waitcnt lgkmcnt(0)
	v_mul_f32_e32 v1, v25, v1
	v_mul_f32_e32 v1, v1, v0
	v_cndmask_b32_e64 v1, 0, v1, s[36:37]
	v_mul_f32_e32 v0, v9, v0
	v_readlane_b32 s36, v246, 21
	v_cvt_pk_bf16_f32 v0, v0, s0
	v_readlane_b32 s37, v246, 22
	ds_write_b32 v162, v1 offset:4624
	s_nop 0
	v_cndmask_b32_e64 v2, v0, 0, s[36:37]
	v_lshl_add_u64 v[0:1], v[88:89], 1, s[42:43]
	global_store_short v[0:1], v2, off sc1
	ds_read_b32 v0, v143
	ds_read_b32 v1, v144
	s_waitcnt lgkmcnt(1)
	v_sub_f32_e32 v0, v0, v166
	v_mul_f32_e32 v0, 0x3fb8aa3b, v0
	v_exp_f32_e32 v0, v0
	s_waitcnt lgkmcnt(0)
	v_mul_f32_e32 v1, v26, v1
	v_mul_f32_e32 v1, v1, v0
	v_mul_f32_e32 v0, v10, v0
	v_cndmask_b32_e64 v1, 0, v1, s[10:11]
	v_cvt_pk_bf16_f32 v0, v0, s0
	ds_write_b32 v162, v1 offset:4896
	v_cndmask_b32_e64 v2, v0, 0, s[12:13]
	v_lshl_add_u64 v[0:1], v[90:91], 1, s[42:43]
	global_store_short v[0:1], v2, off sc1
	ds_read_b32 v0, v145
	ds_read_b32 v1, v146
	s_waitcnt lgkmcnt(1)
	v_sub_f32_e32 v0, v0, v166
	v_mul_f32_e32 v0, 0x3fb8aa3b, v0
	v_exp_f32_e32 v0, v0
	s_waitcnt lgkmcnt(0)
	v_mul_f32_e32 v1, v27, v1
	v_mul_f32_e32 v1, v1, v0
	v_mul_f32_e32 v0, v11, v0
	v_cndmask_b32_e64 v1, 0, v1, s[14:15]
	v_cvt_pk_bf16_f32 v0, v0, s0
	ds_write_b32 v162, v1 offset:5168
	v_cndmask_b32_e64 v2, v0, 0, s[16:17]
	v_lshl_add_u64 v[0:1], v[92:93], 1, s[42:43]
	global_store_short v[0:1], v2, off sc1
	ds_read_b32 v0, v147
	ds_read_b32 v1, v148
	s_waitcnt lgkmcnt(1)
	v_sub_f32_e32 v0, v0, v166
	v_mul_f32_e32 v0, 0x3fb8aa3b, v0
	v_exp_f32_e32 v0, v0
	s_waitcnt lgkmcnt(0)
	v_mul_f32_e32 v1, v28, v1
	v_mul_f32_e32 v1, v1, v0
	v_mul_f32_e32 v0, v12, v0
	v_cndmask_b32_e64 v1, 0, v1, s[18:19]
	v_cvt_pk_bf16_f32 v0, v0, s0
	ds_write_b32 v162, v1 offset:6528
	v_cndmask_b32_e64 v2, v0, 0, s[20:21]
	v_lshl_add_u64 v[0:1], v[94:95], 1, s[42:43]
	global_store_short v[0:1], v2, off sc1
	ds_read_b32 v0, v149
	ds_read_b32 v1, v150
	s_waitcnt lgkmcnt(1)
	v_sub_f32_e32 v0, v0, v166
	v_mul_f32_e32 v0, 0x3fb8aa3b, v0
	v_exp_f32_e32 v0, v0
	s_waitcnt lgkmcnt(0)
	v_mul_f32_e32 v1, v29, v1
	v_mul_f32_e32 v1, v1, v0
	v_mul_f32_e32 v0, v13, v0
	v_cndmask_b32_e64 v1, 0, v1, s[6:7]
	v_cvt_pk_bf16_f32 v0, v0, s0
	ds_write_b32 v162, v1 offset:6800
	v_cndmask_b32_e64 v2, v0, 0, s[8:9]
	v_lshl_add_u64 v[0:1], v[96:97], 1, s[42:43]
	global_store_short v[0:1], v2, off sc1
	ds_read_b32 v0, v151
	ds_read_b32 v1, v152
	s_waitcnt lgkmcnt(1)
	v_sub_f32_e32 v0, v0, v166
	v_mul_f32_e32 v0, 0x3fb8aa3b, v0
	v_exp_f32_e32 v0, v0
	s_waitcnt lgkmcnt(0)
	v_mul_f32_e32 v1, v30, v1
	v_mul_f32_e32 v1, v1, v0
	v_mul_f32_e32 v0, v14, v0
	v_cndmask_b32_e64 v1, 0, v1, s[22:23]
	v_cvt_pk_bf16_f32 v0, v0, s0
	ds_write_b32 v162, v1 offset:7072
	v_cndmask_b32_e64 v2, v0, 0, s[24:25]
	v_lshl_add_u64 v[0:1], v[98:99], 1, s[42:43]
	global_store_short v[0:1], v2, off sc1
	ds_read_b32 v0, v153
	ds_read_b32 v1, v154
	s_waitcnt lgkmcnt(1)
	v_sub_f32_e32 v0, v0, v166
	v_mul_f32_e32 v0, 0x3fb8aa3b, v0
	v_exp_f32_e32 v0, v0
	s_waitcnt lgkmcnt(0)
	v_mul_f32_e32 v1, v31, v1
	v_mul_f32_e32 v1, v1, v0
	v_mul_f32_e32 v0, v15, v0
	v_cndmask_b32_e64 v1, 0, v1, s[28:29]
	v_cvt_pk_bf16_f32 v0, v0, s0
	ds_write_b32 v162, v1 offset:7344
	v_cndmask_b32_e64 v2, v0, 0, s[30:31]
	v_lshl_add_u64 v[0:1], v[100:101], 1, s[42:43]
	global_store_short v[0:1], v2, off sc1
	s_waitcnt lgkmcnt(0)
	s_barrier
; template <bool SIGNAL>
; __device__ __forceinline__ void phase2(const Params& p, unsigned char* smem, const int lo, const int hi, const int worker, const int nworkers) {
;     ...
;     float* sTc = (float*)sq;
;     if (wave == 0) {
;       float* mycol = sTc + lane * 68;
; #pragma unroll 1
;       for (int blk = 0; blk < 4; ++blk) {
;         const int r0 = blk * 16;
;         float acc[16];
; #pragma unroll
;         for (int r = 0; r < 16; ++r) acc[r] = 0.f;
; #pragma unroll 1
;         for (int j = 0; j < r0; j += 4) {
;           const float4 t4 = *(const float4*)(mycol + j);
; #pragma unroll
;           for (int r = 0; r < 16; ++r) {
;             const float4 m4 = *(const float4*)(sM + (r0 + r) * 68 + j);
;             acc[r] += (m4.x * t4.x + m4.y * t4.y) + (m4.z * t4.z + m4.w * t4.w);
;           }
;         }
;         float tt[16];
; #pragma unroll
;         for (int r = 0; r < 16; ++r) {
;           float s = acc[r];
; #pragma unroll
;           for (int q4 = 0; q4 < r; q4 += 4) {
;             const float4 m4 = *(const float4*)(sM + (r0 + r) * 68 + r0 + q4);
;             s += m4.x * tt[q4];
;             if (q4 + 1 < r) s += m4.y * tt[q4 + 1];
;             if (q4 + 2 < r) s += m4.z * tt[q4 + 2];
;             if (q4 + 3 < r) s += m4.w * tt[q4 + 3];
;           }
;           tt[r] = ((r0 + r == lane) ? 1.f : 0.f) - s;
;         }
; #pragma unroll
;         for (int r = 0; r < 16; r += 4) *(float4*)(mycol + r0 + r) = make_float4(tt[r], tt[r + 1], tt[r + 2], tt[r + 3]);
;       }
;     }
	s_mov_b64 s[42:43], exec
	v_and_b32_e32 v178, 63, v218
	v_readfirstlane_b32 s68, v218
	v_and_b32_e32 v179, 15, v178
	v_lshrrev_b32_e32 v221, 4, v178
	s_nop 1
	s_lshr_b32 s68, s68, 6
	s_mul_i32 s69, s68, 0x1100
	s_mul_i32 s70, s68, 0x500
	s_lshl_b32 s71, s68, 4
	v_mul_u32_u24_e32 v192, 0x110, v179
	v_mul_u32_u24_e32 v213, 0x50, v179
	v_add_u32_e32 v216, s71, v179
	v_add_u32_e32 v212, s69, v192
	v_add_u32_e32 v212, 0x8610, v212
	v_lshl_add_u32 v192, v221, 2, v192
	v_add_u32_e32 v213, s70, v213
	v_add_u32_e32 v213, 0xca10, v213
	v_add_u32_e32 v193, s69, v192
	v_add_u32_e32 v193, 0x8610, v193
	v_add_u32_e32 v192, 16, v192
	v_lshl_add_u32 v214, v221, 4, v213
	v_mov_b32_e32 v215, 0
	v_mov_b32_e32 v196, 0
	v_mov_b32_e32 v197, 0
	v_mov_b32_e32 v198, 0
	v_mov_b32_e32 v199, 0
	v_mov_b32_e32 v200, 0
	v_mov_b32_e32 v201, 0
	v_mov_b32_e32 v202, 0
	v_mov_b32_e32 v203, 0
	v_mov_b32_e32 v204, 0
	v_mov_b32_e32 v205, 0
	v_mov_b32_e32 v206, 0
	v_mov_b32_e32 v207, 0
	v_mov_b32_e32 v208, 0
	v_mov_b32_e32 v209, 0
	v_mov_b32_e32 v210, 0
	v_mov_b32_e32 v211, 0
	ds_read_b128 v[222:225], v215 offset:288
	v_cmp_eq_u32_e32 vcc, 0, v216
	s_nop 1
	v_cndmask_b32_e64 v178, 0, 1.0, vcc
	v_sub_f32_e32 v196, v178, v196
	ds_read_b128 v[238:241], v215 offset:560
	v_cmp_eq_u32_e32 vcc, 1, v216
	s_waitcnt lgkmcnt(1)
	v_fmac_f32_e32 v197, v222, v196
	s_nop 0
	v_cndmask_b32_e64 v178, 0, 1.0, vcc
	v_sub_f32_e32 v197, v178, v197
	ds_read_b128 v[222:225], v215 offset:832
	v_cmp_eq_u32_e32 vcc, 2, v216
	s_waitcnt lgkmcnt(1)
	v_fmac_f32_e32 v198, v238, v196
	v_fmac_f32_e32 v198, v239, v197
	v_cndmask_b32_e64 v178, 0, 1.0, vcc
	v_sub_f32_e32 v198, v178, v198
	ds_read_b128 v[238:241], v215 offset:1104
	v_cmp_eq_u32_e32 vcc, 3, v216
	s_waitcnt lgkmcnt(1)
	v_fmac_f32_e32 v199, v222, v196
	v_fmac_f32_e32 v199, v223, v197
	v_fmac_f32_e32 v199, v224, v198
	v_cndmask_b32_e64 v178, 0, 1.0, vcc
	v_sub_f32_e32 v199, v178, v199
	ds_read_b128 v[222:225], v215 offset:1376
	ds_read_b128 v[226:229], v215 offset:1392
	v_cmp_eq_u32_e32 vcc, 4, v216
	s_waitcnt lgkmcnt(2)
	v_fmac_f32_e32 v200, v238, v196
	v_fmac_f32_e32 v200, v239, v197
	v_fmac_f32_e32 v200, v240, v198
	v_fmac_f32_e32 v200, v241, v199
	v_cndmask_b32_e64 v178, 0, 1.0, vcc
	v_sub_f32_e32 v200, v178, v200
	ds_read_b128 v[238:241], v215 offset:1648
	ds_read_b128 v[242:245], v215 offset:1664
	v_cmp_eq_u32_e32 vcc, 5, v216
	s_waitcnt lgkmcnt(2)
	v_fmac_f32_e32 v201, v222, v196
	v_fmac_f32_e32 v201, v223, v197
	v_fmac_f32_e32 v201, v224, v198
	v_fmac_f32_e32 v201, v225, v199
	v_fmac_f32_e32 v201, v226, v200
	v_cndmask_b32_e64 v178, 0, 1.0, vcc
	v_sub_f32_e32 v201, v178, v201
	ds_read_b128 v[222:225], v215 offset:1920
	ds_read_b128 v[226:229], v215 offset:1936
	v_cmp_eq_u32_e32 vcc, 6, v216
	s_waitcnt lgkmcnt(2)
	v_fmac_f32_e32 v202, v238, v196
	v_fmac_f32_e32 v202, v239, v197
	v_fmac_f32_e32 v202, v240, v198
	v_fmac_f32_e32 v202, v241, v199
	v_fmac_f32_e32 v202, v242, v200
	v_fmac_f32_e32 v202, v243, v201
	v_cndmask_b32_e64 v178, 0, 1.0, vcc
	v_sub_f32_e32 v202, v178, v202
	ds_read_b128 v[238:241], v215 offset:2192
	ds_read_b128 v[242:245], v215 offset:2208
	v_cmp_eq_u32_e32 vcc, 7, v216
	s_waitcnt lgkmcnt(2)
	v_fmac_f32_e32 v203, v222, v196
	v_fmac_f32_e32 v203, v223, v197
	v_fmac_f32_e32 v203, v224, v198
	v_fmac_f32_e32 v203, v225, v199
	v_fmac_f32_e32 v203, v226, v200
	v_fmac_f32_e32 v203, v227, v201
	v_fmac_f32_e32 v203, v228, v202
	v_cndmask_b32_e64 v178, 0, 1.0, vcc
	v_sub_f32_e32 v203, v178, v203
	ds_read_b128 v[222:225], v215 offset:2464
	ds_read_b128 v[226:229], v215 offset:2480
	ds_read_b128 v[230:233], v215 offset:2496
	v_cmp_eq_u32_e32 vcc, 8, v216
	s_waitcnt lgkmcnt(3)
	v_fmac_f32_e32 v204, v238, v196
	v_fmac_f32_e32 v204, v239, v197
	v_fmac_f32_e32 v204, v240, v198
	v_fmac_f32_e32 v204, v241, v199
	v_fmac_f32_e32 v204, v242, v200
	v_fmac_f32_e32 v204, v243, v201
	v_fmac_f32_e32 v204, v244, v202
	v_fmac_f32_e32 v204, v245, v203
	v_cndmask_b32_e64 v178, 0, 1.0, vcc
	v_sub_f32_e32 v204, v178, v204
	ds_read_b128 v[238:241], v215 offset:2736
	ds_read_b128 v[242:245], v215 offset:2752
	ds_read_b128 v[248:251], v215 offset:2768
	v_cmp_eq_u32_e32 vcc, 9, v216
	s_waitcnt lgkmcnt(3)
	v_fmac_f32_e32 v205, v222, v196
	v_fmac_f32_e32 v205, v223, v197
	v_fmac_f32_e32 v205, v224, v198
	v_fmac_f32_e32 v205, v225, v199
	v_fmac_f32_e32 v205, v226, v200
	v_fmac_f32_e32 v205, v227, v201
	v_fmac_f32_e32 v205, v228, v202
	v_fmac_f32_e32 v205, v229, v203
	v_fmac_f32_e32 v205, v230, v204
	v_cndmask_b32_e64 v178, 0, 1.0, vcc
	v_sub_f32_e32 v205, v178, v205
	ds_read_b128 v[222:225], v215 offset:3008
	ds_read_b128 v[226:229], v215 offset:3024
	ds_read_b128 v[230:233], v215 offset:3040
	v_cmp_eq_u32_e32 vcc, 10, v216
	s_waitcnt lgkmcnt(3)
	v_fmac_f32_e32 v206, v238, v196
	v_fmac_f32_e32 v206, v239, v197
	v_fmac_f32_e32 v206, v240, v198
	v_fmac_f32_e32 v206, v241, v199
	v_fmac_f32_e32 v206, v242, v200
	v_fmac_f32_e32 v206, v243, v201
	v_fmac_f32_e32 v206, v244, v202
	v_fmac_f32_e32 v206, v245, v203
	v_fmac_f32_e32 v206, v248, v204
	v_fmac_f32_e32 v206, v249, v205
	v_cndmask_b32_e64 v178, 0, 1.0, vcc
	v_sub_f32_e32 v206, v178, v206
	ds_read_b128 v[238:241], v215 offset:3280
	ds_read_b128 v[242:245], v215 offset:3296
	ds_read_b128 v[248:251], v215 offset:3312
	v_cmp_eq_u32_e32 vcc, 11, v216
	s_waitcnt lgkmcnt(3)
	v_fmac_f32_e32 v207, v222, v196
	v_fmac_f32_e32 v207, v223, v197
	v_fmac_f32_e32 v207, v224, v198
	v_fmac_f32_e32 v207, v225, v199
	v_fmac_f32_e32 v207, v226, v200
	v_fmac_f32_e32 v207, v227, v201
	v_fmac_f32_e32 v207, v228, v202
	v_fmac_f32_e32 v207, v229, v203
	v_fmac_f32_e32 v207, v230, v204
	v_fmac_f32_e32 v207, v231, v205
	v_fmac_f32_e32 v207, v232, v206
	v_cndmask_b32_e64 v178, 0, 1.0, vcc
	v_sub_f32_e32 v207, v178, v207
	ds_read_b128 v[222:225], v215 offset:3552
	ds_read_b128 v[226:229], v215 offset:3568
	ds_read_b128 v[230:233], v215 offset:3584
	ds_read_b128 v[234:237], v215 offset:3600
	v_cmp_eq_u32_e32 vcc, 12, v216
	s_waitcnt lgkmcnt(4)
; template <bool SIGNAL>
; __device__ __forceinline__ void phase2(const Params& p, unsigned char* smem, const int lo, const int hi, const int worker, const int nworkers) {
;     ...
;     float* sTc = (float*)sq;
;     if (wave == 0) {
;       float* mycol = sTc + lane * 68;
; #pragma unroll 1
;       for (int blk = 0; blk < 4; ++blk) {
;         const int r0 = blk * 16;
;         float acc[16];
; #pragma unroll
;         for (int r = 0; r < 16; ++r) acc[r] = 0.f;
; #pragma unroll 1
;         for (int j = 0; j < r0; j += 4) {
;           const float4 t4 = *(const float4*)(mycol + j);
; #pragma unroll
;           for (int r = 0; r < 16; ++r) {
;             const float4 m4 = *(const float4*)(sM + (r0 + r) * 68 + j);
;             acc[r] += (m4.x * t4.x + m4.y * t4.y) + (m4.z * t4.z + m4.w * t4.w);
;           }
;         }
;         float tt[16];
; #pragma unroll
;         for (int r = 0; r < 16; ++r) {
;           float s = acc[r];
; #pragma unroll
;           for (int q4 = 0; q4 < r; q4 += 4) {
;             const float4 m4 = *(const float4*)(sM + (r0 + r) * 68 + r0 + q4);
;             s += m4.x * tt[q4];
;             if (q4 + 1 < r) s += m4.y * tt[q4 + 1];
;             if (q4 + 2 < r) s += m4.z * tt[q4 + 2];
;             if (q4 + 3 < r) s += m4.w * tt[q4 + 3];
;           }
;           tt[r] = ((r0 + r == lane) ? 1.f : 0.f) - s;
;         }
; #pragma unroll
;         for (int r = 0; r < 16; r += 4) *(float4*)(mycol + r0 + r) = make_float4(tt[r], tt[r + 1], tt[r + 2], tt[r + 3]);
;       }
;     }
	v_fmac_f32_e32 v208, v238, v196
	v_fmac_f32_e32 v208, v239, v197
	v_fmac_f32_e32 v208, v240, v198
	v_fmac_f32_e32 v208, v241, v199
	v_fmac_f32_e32 v208, v242, v200
	v_fmac_f32_e32 v208, v243, v201
	v_fmac_f32_e32 v208, v244, v202
	v_fmac_f32_e32 v208, v245, v203
	v_fmac_f32_e32 v208, v248, v204
	v_fmac_f32_e32 v208, v249, v205
	v_fmac_f32_e32 v208, v250, v206
	v_fmac_f32_e32 v208, v251, v207
	v_cndmask_b32_e64 v178, 0, 1.0, vcc
	v_sub_f32_e32 v208, v178, v208
	ds_read_b128 v[238:241], v215 offset:3824
	ds_read_b128 v[242:245], v215 offset:3840
	ds_read_b128 v[248:251], v215 offset:3856
	ds_read_b128 v[252:255], v215 offset:3872
	v_cmp_eq_u32_e32 vcc, 13, v216
	s_waitcnt lgkmcnt(4)
	v_fmac_f32_e32 v209, v222, v196
	v_fmac_f32_e32 v209, v223, v197
	v_fmac_f32_e32 v209, v224, v198
	v_fmac_f32_e32 v209, v225, v199
	v_fmac_f32_e32 v209, v226, v200
	v_fmac_f32_e32 v209, v227, v201
	v_fmac_f32_e32 v209, v228, v202
	v_fmac_f32_e32 v209, v229, v203
	v_fmac_f32_e32 v209, v230, v204
	v_fmac_f32_e32 v209, v231, v205
	v_fmac_f32_e32 v209, v232, v206
	v_fmac_f32_e32 v209, v233, v207
	v_fmac_f32_e32 v209, v234, v208
	v_cndmask_b32_e64 v178, 0, 1.0, vcc
	v_sub_f32_e32 v209, v178, v209
	ds_read_b128 v[222:225], v215 offset:4096
	ds_read_b128 v[226:229], v215 offset:4112
	ds_read_b128 v[230:233], v215 offset:4128
	ds_read_b128 v[234:237], v215 offset:4144
	v_cmp_eq_u32_e32 vcc, 14, v216
	s_waitcnt lgkmcnt(4)
	v_fmac_f32_e32 v210, v238, v196
	v_fmac_f32_e32 v210, v239, v197
	v_fmac_f32_e32 v210, v240, v198
	v_fmac_f32_e32 v210, v241, v199
	v_fmac_f32_e32 v210, v242, v200
	v_fmac_f32_e32 v210, v243, v201
	v_fmac_f32_e32 v210, v244, v202
	v_fmac_f32_e32 v210, v245, v203
	v_fmac_f32_e32 v210, v248, v204
	v_fmac_f32_e32 v210, v249, v205
	v_fmac_f32_e32 v210, v250, v206
	v_fmac_f32_e32 v210, v251, v207
	v_fmac_f32_e32 v210, v252, v208
	v_fmac_f32_e32 v210, v253, v209
	v_cndmask_b32_e64 v178, 0, 1.0, vcc
	v_sub_f32_e32 v210, v178, v210
	v_cmp_eq_u32_e32 vcc, 15, v216
	s_waitcnt lgkmcnt(0)
	v_fmac_f32_e32 v211, v222, v196
	v_fmac_f32_e32 v211, v223, v197
	v_fmac_f32_e32 v211, v224, v198
	v_fmac_f32_e32 v211, v225, v199
	v_fmac_f32_e32 v211, v226, v200
	v_fmac_f32_e32 v211, v227, v201
	v_fmac_f32_e32 v211, v228, v202
	v_fmac_f32_e32 v211, v229, v203
	v_fmac_f32_e32 v211, v230, v204
	v_fmac_f32_e32 v211, v231, v205
	v_fmac_f32_e32 v211, v232, v206
	v_fmac_f32_e32 v211, v233, v207
	v_fmac_f32_e32 v211, v234, v208
	v_fmac_f32_e32 v211, v235, v209
	v_fmac_f32_e32 v211, v236, v210
	v_cndmask_b32_e64 v178, 0, 1.0, vcc
	v_sub_f32_e32 v211, v178, v211
	ds_write_b128 v212, v[196:199] offset:0
	ds_write_b128 v212, v[200:203] offset:16
	ds_write_b128 v212, v[204:207] offset:32
	ds_write_b128 v212, v[208:211] offset:48
	s_waitcnt lgkmcnt(0)
	ds_read_b32 v222, v192 offset:4352
	ds_read_b32 v238, v193 offset:0
	ds_read_b32 v223, v192 offset:4368
	ds_read_b32 v239, v193 offset:16
	ds_read_b32 v224, v192 offset:4384
	ds_read_b32 v240, v193 offset:32
	ds_read_b32 v225, v192 offset:4400
	ds_read_b32 v241, v193 offset:48
	s_waitcnt lgkmcnt(0)
	v_mfma_f32_16x16x4_f32 v[180:183], v222, v238, 0
	v_mfma_f32_16x16x4_f32 v[180:183], v223, v239, v[180:183]
	v_mfma_f32_16x16x4_f32 v[180:183], v224, v240, v[180:183]
	v_mfma_f32_16x16x4_f32 v[180:183], v225, v241, v[180:183]
	s_nop 7
	s_nop 7
	ds_write_b128 v214, v[180:183]
	s_waitcnt lgkmcnt(0)
	ds_read_b128 v[196:199], v213
	ds_read_b128 v[200:203], v213 offset:16
	ds_read_b128 v[204:207], v213 offset:32
	ds_read_b128 v[208:211], v213 offset:48
	s_waitcnt lgkmcnt(0)
	ds_read_b128 v[222:225], v215 offset:4704
	v_cmp_eq_u32_e32 vcc, 16, v216
	s_nop 1
	v_cndmask_b32_e64 v178, 0, 1.0, vcc
	v_sub_f32_e32 v196, v178, v196
	ds_read_b128 v[238:241], v215 offset:4976
	v_cmp_eq_u32_e32 vcc, 17, v216
	s_waitcnt lgkmcnt(1)
	v_fmac_f32_e32 v197, v222, v196
	s_nop 0
	v_cndmask_b32_e64 v178, 0, 1.0, vcc
	v_sub_f32_e32 v197, v178, v197
	ds_read_b128 v[222:225], v215 offset:5248
	v_cmp_eq_u32_e32 vcc, 18, v216
	s_waitcnt lgkmcnt(1)
	v_fmac_f32_e32 v198, v238, v196
	v_fmac_f32_e32 v198, v239, v197
	v_cndmask_b32_e64 v178, 0, 1.0, vcc
	v_sub_f32_e32 v198, v178, v198
	ds_read_b128 v[238:241], v215 offset:5520
	v_cmp_eq_u32_e32 vcc, 19, v216
	s_waitcnt lgkmcnt(1)
	v_fmac_f32_e32 v199, v222, v196
	v_fmac_f32_e32 v199, v223, v197
	v_fmac_f32_e32 v199, v224, v198
	v_cndmask_b32_e64 v178, 0, 1.0, vcc
	v_sub_f32_e32 v199, v178, v199
	ds_read_b128 v[222:225], v215 offset:5792
	ds_read_b128 v[226:229], v215 offset:5808
	v_cmp_eq_u32_e32 vcc, 20, v216
	s_waitcnt lgkmcnt(2)
	v_fmac_f32_e32 v200, v238, v196
	v_fmac_f32_e32 v200, v239, v197
	v_fmac_f32_e32 v200, v240, v198
	v_fmac_f32_e32 v200, v241, v199
	v_cndmask_b32_e64 v178, 0, 1.0, vcc
	v_sub_f32_e32 v200, v178, v200
	ds_read_b128 v[238:241], v215 offset:6064
	ds_read_b128 v[242:245], v215 offset:6080
	v_cmp_eq_u32_e32 vcc, 21, v216
	s_waitcnt lgkmcnt(2)
	v_fmac_f32_e32 v201, v222, v196
	v_fmac_f32_e32 v201, v223, v197
	v_fmac_f32_e32 v201, v224, v198
	v_fmac_f32_e32 v201, v225, v199
	v_fmac_f32_e32 v201, v226, v200
	v_cndmask_b32_e64 v178, 0, 1.0, vcc
	v_sub_f32_e32 v201, v178, v201
	ds_read_b128 v[222:225], v215 offset:6336
	ds_read_b128 v[226:229], v215 offset:6352
	v_cmp_eq_u32_e32 vcc, 22, v216
	s_waitcnt lgkmcnt(2)
	v_fmac_f32_e32 v202, v238, v196
	v_fmac_f32_e32 v202, v239, v197
	v_fmac_f32_e32 v202, v240, v198
	v_fmac_f32_e32 v202, v241, v199
	v_fmac_f32_e32 v202, v242, v200
	v_fmac_f32_e32 v202, v243, v201
	v_cndmask_b32_e64 v178, 0, 1.0, vcc
	v_sub_f32_e32 v202, v178, v202
	ds_read_b128 v[238:241], v215 offset:6608
	ds_read_b128 v[242:245], v215 offset:6624
	v_cmp_eq_u32_e32 vcc, 23, v216
	s_waitcnt lgkmcnt(2)
; template <bool SIGNAL>
; __device__ __forceinline__ void phase2(const Params& p, unsigned char* smem, const int lo, const int hi, const int worker, const int nworkers) {
;     ...
;         float tt[16];
; #pragma unroll
;         for (int r = 0; r < 16; ++r) {
;           float s = acc[r];
; #pragma unroll
;           for (int q4 = 0; q4 < r; q4 += 4) {
;             const float4 m4 = *(const float4*)(sM + (r0 + r) * 68 + r0 + q4);
;             s += m4.x * tt[q4];
;             if (q4 + 1 < r) s += m4.y * tt[q4 + 1];
;             if (q4 + 2 < r) s += m4.z * tt[q4 + 2];
;             if (q4 + 3 < r) s += m4.w * tt[q4 + 3];
;           }
;           tt[r] = ((r0 + r == lane) ? 1.f : 0.f) - s;
;         }
; #pragma unroll
;         for (int r = 0; r < 16; r += 4) *(float4*)(mycol + r0 + r) = make_float4(tt[r], tt[r + 1], tt[r + 2], tt[r + 3]);
	v_fmac_f32_e32 v203, v222, v196
	v_fmac_f32_e32 v203, v223, v197
	v_fmac_f32_e32 v203, v224, v198
	v_fmac_f32_e32 v203, v225, v199
	v_fmac_f32_e32 v203, v226, v200
	v_fmac_f32_e32 v203, v227, v201
	v_fmac_f32_e32 v203, v228, v202
	v_cndmask_b32_e64 v178, 0, 1.0, vcc
	v_sub_f32_e32 v203, v178, v203
	ds_read_b128 v[222:225], v215 offset:6880
	ds_read_b128 v[226:229], v215 offset:6896
	ds_read_b128 v[230:233], v215 offset:6912
	v_cmp_eq_u32_e32 vcc, 24, v216
	s_waitcnt lgkmcnt(3)
	v_fmac_f32_e32 v204, v238, v196
	v_fmac_f32_e32 v204, v239, v197
	v_fmac_f32_e32 v204, v240, v198
	v_fmac_f32_e32 v204, v241, v199
	v_fmac_f32_e32 v204, v242, v200
	v_fmac_f32_e32 v204, v243, v201
	v_fmac_f32_e32 v204, v244, v202
	v_fmac_f32_e32 v204, v245, v203
	v_cndmask_b32_e64 v178, 0, 1.0, vcc
	v_sub_f32_e32 v204, v178, v204
	ds_read_b128 v[238:241], v215 offset:7152
	ds_read_b128 v[242:245], v215 offset:7168
	ds_read_b128 v[248:251], v215 offset:7184
	v_cmp_eq_u32_e32 vcc, 25, v216
	s_waitcnt lgkmcnt(3)
	v_fmac_f32_e32 v205, v222, v196
	v_fmac_f32_e32 v205, v223, v197
	v_fmac_f32_e32 v205, v224, v198
	v_fmac_f32_e32 v205, v225, v199
	v_fmac_f32_e32 v205, v226, v200
	v_fmac_f32_e32 v205, v227, v201
	v_fmac_f32_e32 v205, v228, v202
	v_fmac_f32_e32 v205, v229, v203
	v_fmac_f32_e32 v205, v230, v204
	v_cndmask_b32_e64 v178, 0, 1.0, vcc
	v_sub_f32_e32 v205, v178, v205
	ds_read_b128 v[222:225], v215 offset:7424
	ds_read_b128 v[226:229], v215 offset:7440
	ds_read_b128 v[230:233], v215 offset:7456
	v_cmp_eq_u32_e32 vcc, 26, v216
	s_waitcnt lgkmcnt(3)
	v_fmac_f32_e32 v206, v238, v196
	v_fmac_f32_e32 v206, v239, v197
	v_fmac_f32_e32 v206, v240, v198
	v_fmac_f32_e32 v206, v241, v199
	v_fmac_f32_e32 v206, v242, v200
	v_fmac_f32_e32 v206, v243, v201
	v_fmac_f32_e32 v206, v244, v202
	v_fmac_f32_e32 v206, v245, v203
	v_fmac_f32_e32 v206, v248, v204
	v_fmac_f32_e32 v206, v249, v205
	v_cndmask_b32_e64 v178, 0, 1.0, vcc
	v_sub_f32_e32 v206, v178, v206
	ds_read_b128 v[238:241], v215 offset:7696
	ds_read_b128 v[242:245], v215 offset:7712
	ds_read_b128 v[248:251], v215 offset:7728
	v_cmp_eq_u32_e32 vcc, 27, v216
	s_waitcnt lgkmcnt(3)
	v_fmac_f32_e32 v207, v222, v196
	v_fmac_f32_e32 v207, v223, v197
	v_fmac_f32_e32 v207, v224, v198
	v_fmac_f32_e32 v207, v225, v199
	v_fmac_f32_e32 v207, v226, v200
	v_fmac_f32_e32 v207, v227, v201
	v_fmac_f32_e32 v207, v228, v202
	v_fmac_f32_e32 v207, v229, v203
	v_fmac_f32_e32 v207, v230, v204
	v_fmac_f32_e32 v207, v231, v205
	v_fmac_f32_e32 v207, v232, v206
	v_cndmask_b32_e64 v178, 0, 1.0, vcc
	v_sub_f32_e32 v207, v178, v207
	ds_read_b128 v[222:225], v215 offset:7968
	ds_read_b128 v[226:229], v215 offset:7984
	ds_read_b128 v[230:233], v215 offset:8000
	ds_read_b128 v[234:237], v215 offset:8016
	v_cmp_eq_u32_e32 vcc, 28, v216
	s_waitcnt lgkmcnt(4)
	v_fmac_f32_e32 v208, v238, v196
	v_fmac_f32_e32 v208, v239, v197
	v_fmac_f32_e32 v208, v240, v198
	v_fmac_f32_e32 v208, v241, v199
	v_fmac_f32_e32 v208, v242, v200
	v_fmac_f32_e32 v208, v243, v201
	v_fmac_f32_e32 v208, v244, v202
	v_fmac_f32_e32 v208, v245, v203
	v_fmac_f32_e32 v208, v248, v204
	v_fmac_f32_e32 v208, v249, v205
	v_fmac_f32_e32 v208, v250, v206
	v_fmac_f32_e32 v208, v251, v207
	v_cndmask_b32_e64 v178, 0, 1.0, vcc
	v_sub_f32_e32 v208, v178, v208
	ds_read_b128 v[238:241], v215 offset:8240
	ds_read_b128 v[242:245], v215 offset:8256
	ds_read_b128 v[248:251], v215 offset:8272
	ds_read_b128 v[252:255], v215 offset:8288
	v_cmp_eq_u32_e32 vcc, 29, v216
	s_waitcnt lgkmcnt(4)
	v_fmac_f32_e32 v209, v222, v196
	v_fmac_f32_e32 v209, v223, v197
	v_fmac_f32_e32 v209, v224, v198
	v_fmac_f32_e32 v209, v225, v199
	v_fmac_f32_e32 v209, v226, v200
	v_fmac_f32_e32 v209, v227, v201
	v_fmac_f32_e32 v209, v228, v202
	v_fmac_f32_e32 v209, v229, v203
	v_fmac_f32_e32 v209, v230, v204
	v_fmac_f32_e32 v209, v231, v205
	v_fmac_f32_e32 v209, v232, v206
	v_fmac_f32_e32 v209, v233, v207
	v_fmac_f32_e32 v209, v234, v208
	v_cndmask_b32_e64 v178, 0, 1.0, vcc
	v_sub_f32_e32 v209, v178, v209
	ds_read_b128 v[222:225], v215 offset:8512
	ds_read_b128 v[226:229], v215 offset:8528
	ds_read_b128 v[230:233], v215 offset:8544
	ds_read_b128 v[234:237], v215 offset:8560
	v_cmp_eq_u32_e32 vcc, 30, v216
	s_waitcnt lgkmcnt(4)
	v_fmac_f32_e32 v210, v238, v196
	v_fmac_f32_e32 v210, v239, v197
	v_fmac_f32_e32 v210, v240, v198
	v_fmac_f32_e32 v210, v241, v199
	v_fmac_f32_e32 v210, v242, v200
	v_fmac_f32_e32 v210, v243, v201
	v_fmac_f32_e32 v210, v244, v202
	v_fmac_f32_e32 v210, v245, v203
	v_fmac_f32_e32 v210, v248, v204
	v_fmac_f32_e32 v210, v249, v205
	v_fmac_f32_e32 v210, v250, v206
	v_fmac_f32_e32 v210, v251, v207
	v_fmac_f32_e32 v210, v252, v208
	v_fmac_f32_e32 v210, v253, v209
	v_cndmask_b32_e64 v178, 0, 1.0, vcc
	v_sub_f32_e32 v210, v178, v210
	v_cmp_eq_u32_e32 vcc, 31, v216
	s_waitcnt lgkmcnt(0)
	v_fmac_f32_e32 v211, v222, v196
	v_fmac_f32_e32 v211, v223, v197
	v_fmac_f32_e32 v211, v224, v198
	v_fmac_f32_e32 v211, v225, v199
	v_fmac_f32_e32 v211, v226, v200
	v_fmac_f32_e32 v211, v227, v201
	v_fmac_f32_e32 v211, v228, v202
	v_fmac_f32_e32 v211, v229, v203
	v_fmac_f32_e32 v211, v230, v204
	v_fmac_f32_e32 v211, v231, v205
	v_fmac_f32_e32 v211, v232, v206
	v_fmac_f32_e32 v211, v233, v207
	v_fmac_f32_e32 v211, v234, v208
	v_fmac_f32_e32 v211, v235, v209
	v_fmac_f32_e32 v211, v236, v210
	v_cndmask_b32_e64 v178, 0, 1.0, vcc
	v_sub_f32_e32 v211, v178, v211
	ds_write_b128 v212, v[196:199] offset:64
	ds_write_b128 v212, v[200:203] offset:80
	ds_write_b128 v212, v[204:207] offset:96
	ds_write_b128 v212, v[208:211] offset:112
	s_waitcnt lgkmcnt(0)
; template <bool SIGNAL>
; __device__ __forceinline__ void phase2(const Params& p, unsigned char* smem, const int lo, const int hi, const int worker, const int nworkers) {
;     ...
; #pragma unroll 1
;         for (int j = 0; j < r0; j += 4) {
;           const float4 t4 = *(const float4*)(mycol + j);
; #pragma unroll
;           for (int r = 0; r < 16; ++r) {
;             const float4 m4 = *(const float4*)(sM + (r0 + r) * 68 + j);
;             acc[r] += (m4.x * t4.x + m4.y * t4.y) + (m4.z * t4.z + m4.w * t4.w);
;           }
;         }
;         float tt[16];
; #pragma unroll
;         for (int r = 0; r < 16; ++r) {
;           float s = acc[r];
; #pragma unroll
;           for (int q4 = 0; q4 < r; q4 += 4) {
;             const float4 m4 = *(const float4*)(sM + (r0 + r) * 68 + r0 + q4);
;             s += m4.x * tt[q4];
;             if (q4 + 1 < r) s += m4.y * tt[q4 + 1];
;             if (q4 + 2 < r) s += m4.z * tt[q4 + 2];
;             if (q4 + 3 < r) s += m4.w * tt[q4 + 3];
;           }
;           tt[r] = ((r0 + r == lane) ? 1.f : 0.f) - s;
;         }
	ds_read_b32 v222, v192 offset:8704
	ds_read_b32 v238, v193 offset:0
	ds_read_b32 v223, v192 offset:8720
	ds_read_b32 v239, v193 offset:16
	ds_read_b32 v224, v192 offset:8736
	ds_read_b32 v240, v193 offset:32
	ds_read_b32 v225, v192 offset:8752
	ds_read_b32 v241, v193 offset:48
	ds_read_b32 v226, v192 offset:8768
	ds_read_b32 v242, v193 offset:64
	ds_read_b32 v227, v192 offset:8784
	ds_read_b32 v243, v193 offset:80
	s_waitcnt lgkmcnt(0)
	v_mfma_f32_16x16x4_f32 v[180:183], v222, v238, 0
	v_mfma_f32_16x16x4_f32 v[180:183], v223, v239, v[180:183]
	v_mfma_f32_16x16x4_f32 v[180:183], v224, v240, v[180:183]
	v_mfma_f32_16x16x4_f32 v[180:183], v225, v241, v[180:183]
	v_mfma_f32_16x16x4_f32 v[180:183], v226, v242, v[180:183]
	v_mfma_f32_16x16x4_f32 v[180:183], v227, v243, v[180:183]
	ds_read_b32 v228, v192 offset:8800
	ds_read_b32 v244, v193 offset:96
	ds_read_b32 v229, v192 offset:8816
	ds_read_b32 v245, v193 offset:112
	s_waitcnt lgkmcnt(0)
	v_mfma_f32_16x16x4_f32 v[180:183], v228, v244, v[180:183]
	v_mfma_f32_16x16x4_f32 v[180:183], v229, v245, v[180:183]
	s_nop 7
	s_nop 7
	ds_write_b128 v214, v[180:183]
	s_waitcnt lgkmcnt(0)
	ds_read_b128 v[196:199], v213
	ds_read_b128 v[200:203], v213 offset:16
	ds_read_b128 v[204:207], v213 offset:32
	ds_read_b128 v[208:211], v213 offset:48
	s_waitcnt lgkmcnt(0)
	ds_read_b128 v[222:225], v215 offset:9120
	v_cmp_eq_u32_e32 vcc, 32, v216
	s_nop 1
	v_cndmask_b32_e64 v178, 0, 1.0, vcc
	v_sub_f32_e32 v196, v178, v196
	ds_read_b128 v[238:241], v215 offset:9392
	v_cmp_eq_u32_e32 vcc, 33, v216
	s_waitcnt lgkmcnt(1)
	v_fmac_f32_e32 v197, v222, v196
	s_nop 0
	v_cndmask_b32_e64 v178, 0, 1.0, vcc
	v_sub_f32_e32 v197, v178, v197
	ds_read_b128 v[222:225], v215 offset:9664
	v_cmp_eq_u32_e32 vcc, 34, v216
	s_waitcnt lgkmcnt(1)
	v_fmac_f32_e32 v198, v238, v196
	v_fmac_f32_e32 v198, v239, v197
	v_cndmask_b32_e64 v178, 0, 1.0, vcc
	v_sub_f32_e32 v198, v178, v198
	ds_read_b128 v[238:241], v215 offset:9936
	v_cmp_eq_u32_e32 vcc, 35, v216
	s_waitcnt lgkmcnt(1)
	v_fmac_f32_e32 v199, v222, v196
	v_fmac_f32_e32 v199, v223, v197
	v_fmac_f32_e32 v199, v224, v198
	v_cndmask_b32_e64 v178, 0, 1.0, vcc
	v_sub_f32_e32 v199, v178, v199
	ds_read_b128 v[222:225], v215 offset:10208
	ds_read_b128 v[226:229], v215 offset:10224
	v_cmp_eq_u32_e32 vcc, 36, v216
	s_waitcnt lgkmcnt(2)
	v_fmac_f32_e32 v200, v238, v196
	v_fmac_f32_e32 v200, v239, v197
	v_fmac_f32_e32 v200, v240, v198
	v_fmac_f32_e32 v200, v241, v199
	v_cndmask_b32_e64 v178, 0, 1.0, vcc
	v_sub_f32_e32 v200, v178, v200
	ds_read_b128 v[238:241], v215 offset:10480
	ds_read_b128 v[242:245], v215 offset:10496
	v_cmp_eq_u32_e32 vcc, 37, v216
	s_waitcnt lgkmcnt(2)
	v_fmac_f32_e32 v201, v222, v196
	v_fmac_f32_e32 v201, v223, v197
	v_fmac_f32_e32 v201, v224, v198
	v_fmac_f32_e32 v201, v225, v199
	v_fmac_f32_e32 v201, v226, v200
	v_cndmask_b32_e64 v178, 0, 1.0, vcc
	v_sub_f32_e32 v201, v178, v201
	ds_read_b128 v[222:225], v215 offset:10752
	ds_read_b128 v[226:229], v215 offset:10768
	v_cmp_eq_u32_e32 vcc, 38, v216
	s_waitcnt lgkmcnt(2)
	v_fmac_f32_e32 v202, v238, v196
	v_fmac_f32_e32 v202, v239, v197
	v_fmac_f32_e32 v202, v240, v198
	v_fmac_f32_e32 v202, v241, v199
	v_fmac_f32_e32 v202, v242, v200
	v_fmac_f32_e32 v202, v243, v201
	v_cndmask_b32_e64 v178, 0, 1.0, vcc
	v_sub_f32_e32 v202, v178, v202
	ds_read_b128 v[238:241], v215 offset:11024
	ds_read_b128 v[242:245], v215 offset:11040
	v_cmp_eq_u32_e32 vcc, 39, v216
	s_waitcnt lgkmcnt(2)
	v_fmac_f32_e32 v203, v222, v196
	v_fmac_f32_e32 v203, v223, v197
	v_fmac_f32_e32 v203, v224, v198
	v_fmac_f32_e32 v203, v225, v199
	v_fmac_f32_e32 v203, v226, v200
	v_fmac_f32_e32 v203, v227, v201
	v_fmac_f32_e32 v203, v228, v202
	v_cndmask_b32_e64 v178, 0, 1.0, vcc
	v_sub_f32_e32 v203, v178, v203
	ds_read_b128 v[222:225], v215 offset:11296
	ds_read_b128 v[226:229], v215 offset:11312
	ds_read_b128 v[230:233], v215 offset:11328
	v_cmp_eq_u32_e32 vcc, 40, v216
	s_waitcnt lgkmcnt(3)
	v_fmac_f32_e32 v204, v238, v196
	v_fmac_f32_e32 v204, v239, v197
	v_fmac_f32_e32 v204, v240, v198
	v_fmac_f32_e32 v204, v241, v199
	v_fmac_f32_e32 v204, v242, v200
	v_fmac_f32_e32 v204, v243, v201
	v_fmac_f32_e32 v204, v244, v202
	v_fmac_f32_e32 v204, v245, v203
	v_cndmask_b32_e64 v178, 0, 1.0, vcc
	v_sub_f32_e32 v204, v178, v204
	ds_read_b128 v[238:241], v215 offset:11568
	ds_read_b128 v[242:245], v215 offset:11584
	ds_read_b128 v[248:251], v215 offset:11600
	v_cmp_eq_u32_e32 vcc, 41, v216
	s_waitcnt lgkmcnt(3)
	v_fmac_f32_e32 v205, v222, v196
	v_fmac_f32_e32 v205, v223, v197
	v_fmac_f32_e32 v205, v224, v198
	v_fmac_f32_e32 v205, v225, v199
	v_fmac_f32_e32 v205, v226, v200
	v_fmac_f32_e32 v205, v227, v201
	v_fmac_f32_e32 v205, v228, v202
	v_fmac_f32_e32 v205, v229, v203
	v_fmac_f32_e32 v205, v230, v204
	v_cndmask_b32_e64 v178, 0, 1.0, vcc
	v_sub_f32_e32 v205, v178, v205
	ds_read_b128 v[222:225], v215 offset:11840
	ds_read_b128 v[226:229], v215 offset:11856
	ds_read_b128 v[230:233], v215 offset:11872
	v_cmp_eq_u32_e32 vcc, 42, v216
	s_waitcnt lgkmcnt(3)
	v_fmac_f32_e32 v206, v238, v196
	v_fmac_f32_e32 v206, v239, v197
	v_fmac_f32_e32 v206, v240, v198
	v_fmac_f32_e32 v206, v241, v199
	v_fmac_f32_e32 v206, v242, v200
	v_fmac_f32_e32 v206, v243, v201
	v_fmac_f32_e32 v206, v244, v202
	v_fmac_f32_e32 v206, v245, v203
	v_fmac_f32_e32 v206, v248, v204
	v_fmac_f32_e32 v206, v249, v205
	v_cndmask_b32_e64 v178, 0, 1.0, vcc
	v_sub_f32_e32 v206, v178, v206
	ds_read_b128 v[238:241], v215 offset:12112
	ds_read_b128 v[242:245], v215 offset:12128
	ds_read_b128 v[248:251], v215 offset:12144
	v_cmp_eq_u32_e32 vcc, 43, v216
	s_waitcnt lgkmcnt(3)
; template <bool SIGNAL>
; __device__ __forceinline__ void phase2(const Params& p, unsigned char* smem, const int lo, const int hi, const int worker, const int nworkers) {
;     ...
;       for (int blk = 0; blk < 4; ++blk) {
;         const int r0 = blk * 16;
;         float acc[16];
; #pragma unroll
;         for (int r = 0; r < 16; ++r) acc[r] = 0.f;
; #pragma unroll 1
;         for (int j = 0; j < r0; j += 4) {
;           const float4 t4 = *(const float4*)(mycol + j);
; #pragma unroll
;           for (int r = 0; r < 16; ++r) {
;             const float4 m4 = *(const float4*)(sM + (r0 + r) * 68 + j);
;             acc[r] += (m4.x * t4.x + m4.y * t4.y) + (m4.z * t4.z + m4.w * t4.w);
;           }
;         }
;         float tt[16];
; #pragma unroll
;         for (int r = 0; r < 16; ++r) {
;           float s = acc[r];
; #pragma unroll
;           for (int q4 = 0; q4 < r; q4 += 4) {
;             const float4 m4 = *(const float4*)(sM + (r0 + r) * 68 + r0 + q4);
;             s += m4.x * tt[q4];
;             if (q4 + 1 < r) s += m4.y * tt[q4 + 1];
;             if (q4 + 2 < r) s += m4.z * tt[q4 + 2];
;             if (q4 + 3 < r) s += m4.w * tt[q4 + 3];
;           }
;           tt[r] = ((r0 + r == lane) ? 1.f : 0.f) - s;
;         }
; #pragma unroll
;         for (int r = 0; r < 16; r += 4) *(float4*)(mycol + r0 + r) = make_float4(tt[r], tt[r + 1], tt[r + 2], tt[r + 3]);
	v_fmac_f32_e32 v207, v222, v196
	v_fmac_f32_e32 v207, v223, v197
	v_fmac_f32_e32 v207, v224, v198
	v_fmac_f32_e32 v207, v225, v199
	v_fmac_f32_e32 v207, v226, v200
	v_fmac_f32_e32 v207, v227, v201
	v_fmac_f32_e32 v207, v228, v202
	v_fmac_f32_e32 v207, v229, v203
	v_fmac_f32_e32 v207, v230, v204
	v_fmac_f32_e32 v207, v231, v205
	v_fmac_f32_e32 v207, v232, v206
	v_cndmask_b32_e64 v178, 0, 1.0, vcc
	v_sub_f32_e32 v207, v178, v207
	ds_read_b128 v[222:225], v215 offset:12384
	ds_read_b128 v[226:229], v215 offset:12400
	ds_read_b128 v[230:233], v215 offset:12416
	ds_read_b128 v[234:237], v215 offset:12432
	v_cmp_eq_u32_e32 vcc, 44, v216
	s_waitcnt lgkmcnt(4)
	v_fmac_f32_e32 v208, v238, v196
	v_fmac_f32_e32 v208, v239, v197
	v_fmac_f32_e32 v208, v240, v198
	v_fmac_f32_e32 v208, v241, v199
	v_fmac_f32_e32 v208, v242, v200
	v_fmac_f32_e32 v208, v243, v201
	v_fmac_f32_e32 v208, v244, v202
	v_fmac_f32_e32 v208, v245, v203
	v_fmac_f32_e32 v208, v248, v204
	v_fmac_f32_e32 v208, v249, v205
	v_fmac_f32_e32 v208, v250, v206
	v_fmac_f32_e32 v208, v251, v207
	v_cndmask_b32_e64 v178, 0, 1.0, vcc
	v_sub_f32_e32 v208, v178, v208
	ds_read_b128 v[238:241], v215 offset:12656
	ds_read_b128 v[242:245], v215 offset:12672
	ds_read_b128 v[248:251], v215 offset:12688
	ds_read_b128 v[252:255], v215 offset:12704
	v_cmp_eq_u32_e32 vcc, 45, v216
	s_waitcnt lgkmcnt(4)
	v_fmac_f32_e32 v209, v222, v196
	v_fmac_f32_e32 v209, v223, v197
	v_fmac_f32_e32 v209, v224, v198
	v_fmac_f32_e32 v209, v225, v199
	v_fmac_f32_e32 v209, v226, v200
	v_fmac_f32_e32 v209, v227, v201
	v_fmac_f32_e32 v209, v228, v202
	v_fmac_f32_e32 v209, v229, v203
	v_fmac_f32_e32 v209, v230, v204
	v_fmac_f32_e32 v209, v231, v205
	v_fmac_f32_e32 v209, v232, v206
	v_fmac_f32_e32 v209, v233, v207
	v_fmac_f32_e32 v209, v234, v208
	v_cndmask_b32_e64 v178, 0, 1.0, vcc
	v_sub_f32_e32 v209, v178, v209
	ds_read_b128 v[222:225], v215 offset:12928
	ds_read_b128 v[226:229], v215 offset:12944
	ds_read_b128 v[230:233], v215 offset:12960
	ds_read_b128 v[234:237], v215 offset:12976
	v_cmp_eq_u32_e32 vcc, 46, v216
	s_waitcnt lgkmcnt(4)
	v_fmac_f32_e32 v210, v238, v196
	v_fmac_f32_e32 v210, v239, v197
	v_fmac_f32_e32 v210, v240, v198
	v_fmac_f32_e32 v210, v241, v199
	v_fmac_f32_e32 v210, v242, v200
	v_fmac_f32_e32 v210, v243, v201
	v_fmac_f32_e32 v210, v244, v202
	v_fmac_f32_e32 v210, v245, v203
	v_fmac_f32_e32 v210, v248, v204
	v_fmac_f32_e32 v210, v249, v205
	v_fmac_f32_e32 v210, v250, v206
	v_fmac_f32_e32 v210, v251, v207
	v_fmac_f32_e32 v210, v252, v208
	v_fmac_f32_e32 v210, v253, v209
	v_cndmask_b32_e64 v178, 0, 1.0, vcc
	v_sub_f32_e32 v210, v178, v210
	v_cmp_eq_u32_e32 vcc, 47, v216
	s_waitcnt lgkmcnt(0)
	v_fmac_f32_e32 v211, v222, v196
	v_fmac_f32_e32 v211, v223, v197
	v_fmac_f32_e32 v211, v224, v198
	v_fmac_f32_e32 v211, v225, v199
	v_fmac_f32_e32 v211, v226, v200
	v_fmac_f32_e32 v211, v227, v201
	v_fmac_f32_e32 v211, v228, v202
	v_fmac_f32_e32 v211, v229, v203
	v_fmac_f32_e32 v211, v230, v204
	v_fmac_f32_e32 v211, v231, v205
	v_fmac_f32_e32 v211, v232, v206
	v_fmac_f32_e32 v211, v233, v207
	v_fmac_f32_e32 v211, v234, v208
	v_fmac_f32_e32 v211, v235, v209
	v_fmac_f32_e32 v211, v236, v210
	v_cndmask_b32_e64 v178, 0, 1.0, vcc
	v_sub_f32_e32 v211, v178, v211
	ds_write_b128 v212, v[196:199] offset:128
	ds_write_b128 v212, v[200:203] offset:144
	ds_write_b128 v212, v[204:207] offset:160
	ds_write_b128 v212, v[208:211] offset:176
	s_waitcnt lgkmcnt(0)
	ds_read_b32 v222, v192 offset:13056
	ds_read_b32 v238, v193 offset:0
	ds_read_b32 v223, v192 offset:13072
	ds_read_b32 v239, v193 offset:16
	ds_read_b32 v224, v192 offset:13088
	ds_read_b32 v240, v193 offset:32
	ds_read_b32 v225, v192 offset:13104
	ds_read_b32 v241, v193 offset:48
	ds_read_b32 v226, v192 offset:13120
	ds_read_b32 v242, v193 offset:64
	ds_read_b32 v227, v192 offset:13136
	ds_read_b32 v243, v193 offset:80
	s_waitcnt lgkmcnt(0)
	v_mfma_f32_16x16x4_f32 v[180:183], v222, v238, 0
	v_mfma_f32_16x16x4_f32 v[180:183], v223, v239, v[180:183]
	v_mfma_f32_16x16x4_f32 v[180:183], v224, v240, v[180:183]
	v_mfma_f32_16x16x4_f32 v[180:183], v225, v241, v[180:183]
	v_mfma_f32_16x16x4_f32 v[180:183], v226, v242, v[180:183]
	v_mfma_f32_16x16x4_f32 v[180:183], v227, v243, v[180:183]
	ds_read_b32 v228, v192 offset:13152
	ds_read_b32 v244, v193 offset:96
	ds_read_b32 v229, v192 offset:13168
	ds_read_b32 v245, v193 offset:112
	ds_read_b32 v230, v192 offset:13184
	ds_read_b32 v248, v193 offset:128
	ds_read_b32 v231, v192 offset:13200
	ds_read_b32 v249, v193 offset:144
	ds_read_b32 v232, v192 offset:13216
	ds_read_b32 v250, v193 offset:160
	ds_read_b32 v233, v192 offset:13232
	ds_read_b32 v251, v193 offset:176
	s_waitcnt lgkmcnt(0)
	v_mfma_f32_16x16x4_f32 v[180:183], v228, v244, v[180:183]
	v_mfma_f32_16x16x4_f32 v[180:183], v229, v245, v[180:183]
	v_mfma_f32_16x16x4_f32 v[180:183], v230, v248, v[180:183]
	v_mfma_f32_16x16x4_f32 v[180:183], v231, v249, v[180:183]
	v_mfma_f32_16x16x4_f32 v[180:183], v232, v250, v[180:183]
	v_mfma_f32_16x16x4_f32 v[180:183], v233, v251, v[180:183]
	s_nop 7
	s_nop 7
	ds_write_b128 v214, v[180:183]
	s_waitcnt lgkmcnt(0)
	ds_read_b128 v[196:199], v213
	ds_read_b128 v[200:203], v213 offset:16
	ds_read_b128 v[204:207], v213 offset:32
	ds_read_b128 v[208:211], v213 offset:48
	s_waitcnt lgkmcnt(0)
	ds_read_b128 v[222:225], v215 offset:13536
	v_cmp_eq_u32_e32 vcc, 48, v216
	s_nop 1
	v_cndmask_b32_e64 v178, 0, 1.0, vcc
	v_sub_f32_e32 v196, v178, v196
	ds_read_b128 v[238:241], v215 offset:13808
	v_cmp_eq_u32_e32 vcc, 49, v216
	s_waitcnt lgkmcnt(1)
	v_fmac_f32_e32 v197, v222, v196
	s_nop 0
	v_cndmask_b32_e64 v178, 0, 1.0, vcc
	v_sub_f32_e32 v197, v178, v197
	ds_read_b128 v[222:225], v215 offset:14080
	v_cmp_eq_u32_e32 vcc, 50, v216
	s_waitcnt lgkmcnt(1)
; template <bool SIGNAL>
; __device__ __forceinline__ void phase2(const Params& p, unsigned char* smem, const int lo, const int hi, const int worker, const int nworkers) {
;     ...
;         float tt[16];
; #pragma unroll
;         for (int r = 0; r < 16; ++r) {
;           float s = acc[r];
; #pragma unroll
;           for (int q4 = 0; q4 < r; q4 += 4) {
;             const float4 m4 = *(const float4*)(sM + (r0 + r) * 68 + r0 + q4);
;             s += m4.x * tt[q4];
;             if (q4 + 1 < r) s += m4.y * tt[q4 + 1];
;             if (q4 + 2 < r) s += m4.z * tt[q4 + 2];
;             if (q4 + 3 < r) s += m4.w * tt[q4 + 3];
;           }
;           tt[r] = ((r0 + r == lane) ? 1.f : 0.f) - s;
;         }
	v_fmac_f32_e32 v198, v238, v196
	v_fmac_f32_e32 v198, v239, v197
	v_cndmask_b32_e64 v178, 0, 1.0, vcc
	v_sub_f32_e32 v198, v178, v198
	ds_read_b128 v[238:241], v215 offset:14352
	v_cmp_eq_u32_e32 vcc, 51, v216
	s_waitcnt lgkmcnt(1)
	v_fmac_f32_e32 v199, v222, v196
	v_fmac_f32_e32 v199, v223, v197
	v_fmac_f32_e32 v199, v224, v198
	v_cndmask_b32_e64 v178, 0, 1.0, vcc
	v_sub_f32_e32 v199, v178, v199
	ds_read_b128 v[222:225], v215 offset:14624
	ds_read_b128 v[226:229], v215 offset:14640
	v_cmp_eq_u32_e32 vcc, 52, v216
	s_waitcnt lgkmcnt(2)
	v_fmac_f32_e32 v200, v238, v196
	v_fmac_f32_e32 v200, v239, v197
	v_fmac_f32_e32 v200, v240, v198
	v_fmac_f32_e32 v200, v241, v199
	v_cndmask_b32_e64 v178, 0, 1.0, vcc
	v_sub_f32_e32 v200, v178, v200
	ds_read_b128 v[238:241], v215 offset:14896
	ds_read_b128 v[242:245], v215 offset:14912
	v_cmp_eq_u32_e32 vcc, 53, v216
	s_waitcnt lgkmcnt(2)
	v_fmac_f32_e32 v201, v222, v196
	v_fmac_f32_e32 v201, v223, v197
	v_fmac_f32_e32 v201, v224, v198
	v_fmac_f32_e32 v201, v225, v199
	v_fmac_f32_e32 v201, v226, v200
	v_cndmask_b32_e64 v178, 0, 1.0, vcc
	v_sub_f32_e32 v201, v178, v201
	ds_read_b128 v[222:225], v215 offset:15168
	ds_read_b128 v[226:229], v215 offset:15184
	v_cmp_eq_u32_e32 vcc, 54, v216
	s_waitcnt lgkmcnt(2)
	v_fmac_f32_e32 v202, v238, v196
	v_fmac_f32_e32 v202, v239, v197
	v_fmac_f32_e32 v202, v240, v198
	v_fmac_f32_e32 v202, v241, v199
	v_fmac_f32_e32 v202, v242, v200
	v_fmac_f32_e32 v202, v243, v201
	v_cndmask_b32_e64 v178, 0, 1.0, vcc
	v_sub_f32_e32 v202, v178, v202
	ds_read_b128 v[238:241], v215 offset:15440
	ds_read_b128 v[242:245], v215 offset:15456
	v_cmp_eq_u32_e32 vcc, 55, v216
	s_waitcnt lgkmcnt(2)
	v_fmac_f32_e32 v203, v222, v196
	v_fmac_f32_e32 v203, v223, v197
	v_fmac_f32_e32 v203, v224, v198
	v_fmac_f32_e32 v203, v225, v199
	v_fmac_f32_e32 v203, v226, v200
	v_fmac_f32_e32 v203, v227, v201
	v_fmac_f32_e32 v203, v228, v202
	v_cndmask_b32_e64 v178, 0, 1.0, vcc
	v_sub_f32_e32 v203, v178, v203
	ds_read_b128 v[222:225], v215 offset:15712
	ds_read_b128 v[226:229], v215 offset:15728
	ds_read_b128 v[230:233], v215 offset:15744
	v_cmp_eq_u32_e32 vcc, 56, v216
	s_waitcnt lgkmcnt(3)
	v_fmac_f32_e32 v204, v238, v196
	v_fmac_f32_e32 v204, v239, v197
	v_fmac_f32_e32 v204, v240, v198
	v_fmac_f32_e32 v204, v241, v199
	v_fmac_f32_e32 v204, v242, v200
	v_fmac_f32_e32 v204, v243, v201
	v_fmac_f32_e32 v204, v244, v202
	v_fmac_f32_e32 v204, v245, v203
	v_cndmask_b32_e64 v178, 0, 1.0, vcc
	v_sub_f32_e32 v204, v178, v204
	ds_read_b128 v[238:241], v215 offset:15984
	ds_read_b128 v[242:245], v215 offset:16000
	ds_read_b128 v[248:251], v215 offset:16016
	v_cmp_eq_u32_e32 vcc, 57, v216
	s_waitcnt lgkmcnt(3)
	v_fmac_f32_e32 v205, v222, v196
	v_fmac_f32_e32 v205, v223, v197
	v_fmac_f32_e32 v205, v224, v198
	v_fmac_f32_e32 v205, v225, v199
	v_fmac_f32_e32 v205, v226, v200
	v_fmac_f32_e32 v205, v227, v201
	v_fmac_f32_e32 v205, v228, v202
	v_fmac_f32_e32 v205, v229, v203
	v_fmac_f32_e32 v205, v230, v204
	v_cndmask_b32_e64 v178, 0, 1.0, vcc
	v_sub_f32_e32 v205, v178, v205
	ds_read_b128 v[222:225], v215 offset:16256
	ds_read_b128 v[226:229], v215 offset:16272
	ds_read_b128 v[230:233], v215 offset:16288
	v_cmp_eq_u32_e32 vcc, 58, v216
	s_waitcnt lgkmcnt(3)
	v_fmac_f32_e32 v206, v238, v196
	v_fmac_f32_e32 v206, v239, v197
	v_fmac_f32_e32 v206, v240, v198
	v_fmac_f32_e32 v206, v241, v199
	v_fmac_f32_e32 v206, v242, v200
	v_fmac_f32_e32 v206, v243, v201
	v_fmac_f32_e32 v206, v244, v202
	v_fmac_f32_e32 v206, v245, v203
	v_fmac_f32_e32 v206, v248, v204
	v_fmac_f32_e32 v206, v249, v205
	v_cndmask_b32_e64 v178, 0, 1.0, vcc
	v_sub_f32_e32 v206, v178, v206
	ds_read_b128 v[238:241], v215 offset:16528
	ds_read_b128 v[242:245], v215 offset:16544
	ds_read_b128 v[248:251], v215 offset:16560
	v_cmp_eq_u32_e32 vcc, 59, v216
	s_waitcnt lgkmcnt(3)
	v_fmac_f32_e32 v207, v222, v196
	v_fmac_f32_e32 v207, v223, v197
	v_fmac_f32_e32 v207, v224, v198
	v_fmac_f32_e32 v207, v225, v199
	v_fmac_f32_e32 v207, v226, v200
	v_fmac_f32_e32 v207, v227, v201
	v_fmac_f32_e32 v207, v228, v202
	v_fmac_f32_e32 v207, v229, v203
	v_fmac_f32_e32 v207, v230, v204
	v_fmac_f32_e32 v207, v231, v205
	v_fmac_f32_e32 v207, v232, v206
	v_cndmask_b32_e64 v178, 0, 1.0, vcc
	v_sub_f32_e32 v207, v178, v207
	ds_read_b128 v[222:225], v215 offset:16800
	ds_read_b128 v[226:229], v215 offset:16816
	ds_read_b128 v[230:233], v215 offset:16832
	ds_read_b128 v[234:237], v215 offset:16848
	v_cmp_eq_u32_e32 vcc, 60, v216
	s_waitcnt lgkmcnt(4)
	v_fmac_f32_e32 v208, v238, v196
	v_fmac_f32_e32 v208, v239, v197
	v_fmac_f32_e32 v208, v240, v198
	v_fmac_f32_e32 v208, v241, v199
	v_fmac_f32_e32 v208, v242, v200
	v_fmac_f32_e32 v208, v243, v201
	v_fmac_f32_e32 v208, v244, v202
	v_fmac_f32_e32 v208, v245, v203
	v_fmac_f32_e32 v208, v248, v204
	v_fmac_f32_e32 v208, v249, v205
	v_fmac_f32_e32 v208, v250, v206
	v_fmac_f32_e32 v208, v251, v207
	v_cndmask_b32_e64 v178, 0, 1.0, vcc
	v_sub_f32_e32 v208, v178, v208
	ds_read_b128 v[238:241], v215 offset:17072
	ds_read_b128 v[242:245], v215 offset:17088
	ds_read_b128 v[248:251], v215 offset:17104
	ds_read_b128 v[252:255], v215 offset:17120
	v_cmp_eq_u32_e32 vcc, 61, v216
	s_waitcnt lgkmcnt(4)
; __device__ __forceinline__ unsigned cvtpk(float lo, float hi) { f32x2_t v = {lo, hi}; bf16x2_t b = __builtin_convertvector(v, bf16x2_t); return __builtin_bit_cast(unsigned, b); }
; template <bool SIGNAL>
; __device__ __forceinline__ void phase2(const Params& p, unsigned char* smem, const int lo, const int hi, const int worker, const int nworkers) {
;     ...
;         for (int r = 0; r < 16; r += 4) *(float4*)(mycol + r0 + r) = make_float4(tt[r], tt[r + 1], tt[r + 2], tt[r + 3]);
;       }
;     }
;     __syncthreads();
; #pragma unroll
;     for (int i = 0; i < 2; ++i) {
;       int idx = tid + 256 * i; int r = idx >> 3, c8 = (idx & 7) * 8; const float* s = sTc + c8 * 68 + r;
;       uint4 o; o.x = cvtpk(s[0], s[68]); o.y = cvtpk(s[136], s[204]); o.z = cvtpk(s[272], s[340]); o.w = cvtpk(s[408], s[476]);
;       *(uint4*)(Tg + r * 64 + c8) = o;
;     }
;     if (tid < 64) {
;       float gc = sgc[tid], be = sbeta[tid]; float eg = __expf(gc);
;       SCg[tid] = be; SCg[64 + tid] = be * eg; SCg[128 + tid] = eg; SCg[192 + tid] = __expf(sgc[63] - gc);
;     }
;     __syncthreads();
;     if (SIGNAL && tid == 0)
;       __hip_atomic_fetch_add((unsigned*)(p.ws + OFF_BAR) + 16 + bh * 17 + (c >> 3), 1u, __ATOMIC_RELEASE, __HIP_MEMORY_SCOPE_AGENT);
	v_fmac_f32_e32 v209, v222, v196
	v_fmac_f32_e32 v209, v223, v197
	v_fmac_f32_e32 v209, v224, v198
	v_fmac_f32_e32 v209, v225, v199
	v_fmac_f32_e32 v209, v226, v200
	v_fmac_f32_e32 v209, v227, v201
	v_fmac_f32_e32 v209, v228, v202
	v_fmac_f32_e32 v209, v229, v203
	v_fmac_f32_e32 v209, v230, v204
	v_fmac_f32_e32 v209, v231, v205
	v_fmac_f32_e32 v209, v232, v206
	v_fmac_f32_e32 v209, v233, v207
	v_fmac_f32_e32 v209, v234, v208
	v_cndmask_b32_e64 v178, 0, 1.0, vcc
	v_sub_f32_e32 v209, v178, v209
	ds_read_b128 v[222:225], v215 offset:17344
	ds_read_b128 v[226:229], v215 offset:17360
	ds_read_b128 v[230:233], v215 offset:17376
	ds_read_b128 v[234:237], v215 offset:17392
	v_cmp_eq_u32_e32 vcc, 62, v216
	s_waitcnt lgkmcnt(4)
	v_fmac_f32_e32 v210, v238, v196
	v_fmac_f32_e32 v210, v239, v197
	v_fmac_f32_e32 v210, v240, v198
	v_fmac_f32_e32 v210, v241, v199
	v_fmac_f32_e32 v210, v242, v200
	v_fmac_f32_e32 v210, v243, v201
	v_fmac_f32_e32 v210, v244, v202
	v_fmac_f32_e32 v210, v245, v203
	v_fmac_f32_e32 v210, v248, v204
	v_fmac_f32_e32 v210, v249, v205
	v_fmac_f32_e32 v210, v250, v206
	v_fmac_f32_e32 v210, v251, v207
	v_fmac_f32_e32 v210, v252, v208
	v_fmac_f32_e32 v210, v253, v209
	v_cndmask_b32_e64 v178, 0, 1.0, vcc
	v_sub_f32_e32 v210, v178, v210
	v_cmp_eq_u32_e32 vcc, 63, v216
	s_waitcnt lgkmcnt(0)
	v_fmac_f32_e32 v211, v222, v196
	v_fmac_f32_e32 v211, v223, v197
	v_fmac_f32_e32 v211, v224, v198
	v_fmac_f32_e32 v211, v225, v199
	v_fmac_f32_e32 v211, v226, v200
	v_fmac_f32_e32 v211, v227, v201
	v_fmac_f32_e32 v211, v228, v202
	v_fmac_f32_e32 v211, v229, v203
	v_fmac_f32_e32 v211, v230, v204
	v_fmac_f32_e32 v211, v231, v205
	v_fmac_f32_e32 v211, v232, v206
	v_fmac_f32_e32 v211, v233, v207
	v_fmac_f32_e32 v211, v234, v208
	v_fmac_f32_e32 v211, v235, v209
	v_fmac_f32_e32 v211, v236, v210
	v_cndmask_b32_e64 v178, 0, 1.0, vcc
	v_sub_f32_e32 v211, v178, v211
	ds_write_b128 v212, v[196:199] offset:192
	ds_write_b128 v212, v[200:203] offset:208
	ds_write_b128 v212, v[204:207] offset:224
	ds_write_b128 v212, v[208:211] offset:240
	s_waitcnt lgkmcnt(0)
.LBB0_305:
	s_or_b64 exec, exec, s[42:43]
	v_lshlrev_b32_e32 v0, 1, v38
	v_mov_b32_e32 v1, v35
	v_lshl_add_u64 v[4:5], s[38:39], 0, v[0:1]
	v_add_u32_e32 v0, 0x8400, v155
	v_add_u32_e32 v6, 0x8800, v155
	s_waitcnt lgkmcnt(0)
	s_barrier
	ds_read2_b32 v[0:1], v0 offset0:128 offset1:196
	ds_read2_b32 v[2:3], v6 offset0:8 offset1:76
	s_waitcnt lgkmcnt(1)
	v_cvt_pk_bf16_f32 v0, v0, v1
	s_waitcnt lgkmcnt(0)
	v_cvt_pk_bf16_f32 v1, v2, v3
	ds_read2_b32 v[2:3], v6 offset0:144 offset1:212
	s_waitcnt lgkmcnt(0)
	v_cvt_pk_bf16_f32 v2, v2, v3
	v_add_u32_e32 v3, 0x8c00, v155
	ds_read2_b32 v[6:7], v3 offset0:24 offset1:92
	s_waitcnt lgkmcnt(0)
	v_cvt_pk_bf16_f32 v3, v6, v7
	v_lshl_add_u64 v[6:7], v[62:63], 1, v[4:5]
	global_store_dwordx4 v[6:7], v[0:3], off sc1
	v_add_u32_e32 v6, 0x8800, v156
	ds_read2_b32 v[2:3], v6 offset0:8 offset1:76
	v_add_u32_e32 v0, 0x8400, v156
	ds_read2_b32 v[0:1], v0 offset0:128 offset1:196
	v_lshl_add_u64 v[4:5], v[64:65], 1, v[4:5]
	s_waitcnt lgkmcnt(0)
	v_cvt_pk_bf16_f32 v0, v0, v1
	v_cvt_pk_bf16_f32 v1, v2, v3
	ds_read2_b32 v[2:3], v6 offset0:144 offset1:212
	s_waitcnt lgkmcnt(0)
	v_cvt_pk_bf16_f32 v2, v2, v3
	v_add_u32_e32 v3, 0x8c00, v156
	ds_read2_b32 v[6:7], v3 offset0:24 offset1:92
	s_waitcnt lgkmcnt(0)
	v_cvt_pk_bf16_f32 v3, v6, v7
	global_store_dwordx4 v[4:5], v[0:3], off sc1
	s_mov_b64 s[42:43], exec
	v_readlane_b32 s36, v247, 9
	v_readlane_b32 s37, v247, 10
	s_and_b64 s[36:37], s[42:43], s[36:37]
	s_mov_b64 exec, s[36:37]
	s_cbranch_execz .LBB0_307
	ds_read_b32 v4, v112
	ds_read_b32 v5, v113
	s_mov_b64 s[36:37], 0x4000
	s_waitcnt lgkmcnt(1)
	v_mul_f32_e32 v0, 0x3fb8aa3b, v4
	v_exp_f32_e32 v6, v0
	v_lshl_add_u64 v[0:1], v[40:41], 2, s[38:39]
	v_lshl_add_u64 v[2:3], v[0:1], 0, s[36:37]
	v_add_co_u32_e32 v0, vcc, 0x4000, v0
	v_readlane_b32 s36, v246, 0
	s_nop 0
	v_addc_co_u32_e32 v1, vcc, 0, v1, vcc
	s_waitcnt lgkmcnt(0)
	global_store_dword v[0:1], v5, off sc1
	v_mul_f32_e32 v0, v5, v6
	global_store_dword v[2:3], v0, off offset:256 sc1
	global_store_dword v[2:3], v6, off offset:512 sc1
	v_mov_b32_e32 v0, s36
	ds_read_b32 v0, v0
	s_waitcnt lgkmcnt(0)
	v_sub_f32_e32 v0, v0, v4
	v_mul_f32_e32 v0, 0x3fb8aa3b, v0
	v_exp_f32_e32 v0, v0
	global_store_dword v[2:3], v0, off offset:768 sc1
.LBB0_307:
	s_or_b64 exec, exec, s[42:43]
	s_waitcnt vmcnt(0)
	s_barrier
	s_mov_b64 s[38:39], exec
	v_readlane_b32 s36, v247, 11
	v_readlane_b32 s37, v247, 12
	s_and_b64 s[36:37], s[38:39], s[36:37]
	s_mov_b64 exec, s[36:37]
	s_cbranch_execz .LBB0_253
	s_mov_b64 s[42:43], exec
	v_mbcnt_lo_u32_b32 v0, s42, 0
	v_mbcnt_hi_u32_b32 v0, s43, v0
	v_cmp_eq_u32_e32 vcc, 0, v0
	s_and_b64 s[36:37], exec, vcc
	s_mov_b64 exec, s[36:37]
	s_cbranch_execz .LBB0_253
	s_mulk_i32 s90, 0x44
	v_readlane_b32 s36, v247, 60
	s_add_u32 s68, s36, s90
	v_readlane_b32 s36, v247, 61
	s_addc_u32 s69, s36, 0
	s_ashr_i32 s36, s84, 7
	s_ashr_i32 s37, s36, 31
	s_lshl_b64 s[36:37], s[36:37], 2
	s_add_u32 s36, s68, s36
	s_addc_u32 s37, s69, s37
	s_bcnt1_i32_b64 s42, s[42:43]
	v_mov_b32_e32 v0, s42
	s_waitcnt vmcnt(0)
	global_atomic_add v35, v0, s[36:37]
	s_branch .LBB0_253
